# phase-6 row pass: loads without the nt hint
# baseline (speedup 1.0000x reference)
.LBB0_93:
	s_andn2_b64 vcc, exec, s[0:1]
	s_cbranch_vccnz .LBB0_141
	s_cmp_gt_i32 s94, 5
	s_mov_b64 s[0:1], -1
	s_cbranch_scc0 .LBB0_113
	v_readlane_b32 s0, v254, 59
	v_readlane_b32 s1, v254, 60
	s_nop 3
	s_load_dword s2, s[0:1], 0x0
	s_waitcnt lgkmcnt(0)
	s_cmpk_lg_u32 s2, 0x100
	s_cbranch_scc1 .Lrow6_generic
	v_readlane_b32 s0, v254, 58
	v_readfirstlane_b32 s1, v197
	v_readlane_b32 s4, v254, 42
	v_readlane_b32 s5, v254, 43
	v_readlane_b32 s6, v254, 44
	v_readlane_b32 s7, v254, 45
	v_readlane_b32 s8, v253, 4
	v_readlane_b32 s9, v253, 5
	v_readlane_b32 s2, v253, 6
	v_readlane_b32 s3, v253, 7
	v_and_b32_e32 v244, 63, v197
	v_lshlrev_b32_e32 v245, 3, v244
	v_lshlrev_b32_e32 v244, 4, v244
	s_lshr_b32 s1, s1, 6
	s_lshl_b32 s0, s0, 3
	s_add_i32 s1, s0, s1
	s_lshl_b32 s0, s1, 11
	s_add_u32 s10, s92, 0xf000000
	s_addc_u32 s11, s93, 0
	s_add_u32 s10, s10, s0
	s_addc_u32 s11, s11, 0
	s_add_u32 s14, s92, 0x17400000
	s_addc_u32 s15, s93, 0
	s_add_u32 s14, s14, s0
	s_addc_u32 s15, s15, 0
	s_lshl_b32 s0, s1, 12
	s_add_u32 s12, s4, s0
	s_addc_u32 s13, s5, 0
	s_add_u32 s18, s6, s0
	s_addc_u32 s19, s7, 0
	s_add_u32 s16, s10, 0x4000000
	s_addc_u32 s17, s11, 0
	s_add_u32 s20, s14, 0x4000000
	s_addc_u32 s21, s15, 0
	global_load_dwordx4 v[180:183], v244, s[8:9] offset:0
	global_load_dwordx4 v[184:187], v244, s[8:9] offset:1024
	global_load_dwordx4 v[188:191], v244, s[8:9] offset:2048
	global_load_dwordx4 v[192:195], v244, s[8:9] offset:3072
	global_load_dwordx4 v[202:205], v244, s[2:3] offset:0
	global_load_dwordx4 v[206:209], v244, s[2:3] offset:1024
	global_load_dwordx4 v[210:213], v244, s[2:3] offset:2048
	global_load_dwordx4 v[214:217], v244, s[2:3] offset:3072
	s_mov_b64 s[22:23], s[10:11]
	s_mov_b64 s[24:25], s[12:13]
	global_load_dwordx2 v[4:5], v245, s[22:23] offset:0
	global_load_dwordx2 v[6:7], v245, s[22:23] offset:512
	global_load_dwordx2 v[8:9], v245, s[22:23] offset:1024
	global_load_dwordx2 v[10:11], v245, s[22:23] offset:1536
	global_load_dwordx4 v[12:15], v244, s[24:25] offset:0
	global_load_dwordx4 v[16:19], v244, s[24:25] offset:1024
	global_load_dwordx4 v[20:23], v244, s[24:25] offset:2048
	global_load_dwordx4 v[24:27], v244, s[24:25] offset:3072
	s_add_u32 s22, s10, 0x400000
	s_addc_u32 s23, s11, 0
	s_add_u32 s24, s12, 0x800000
	s_addc_u32 s25, s13, 0
	global_load_dwordx2 v[28:29], v245, s[22:23] offset:0
	global_load_dwordx2 v[30:31], v245, s[22:23] offset:512
	global_load_dwordx2 v[32:33], v245, s[22:23] offset:1024
	global_load_dwordx2 v[34:35], v245, s[22:23] offset:1536
	global_load_dwordx4 v[36:39], v244, s[24:25] offset:0
	global_load_dwordx4 v[40:43], v244, s[24:25] offset:1024
	global_load_dwordx4 v[44:47], v244, s[24:25] offset:2048
	global_load_dwordx4 v[48:51], v244, s[24:25] offset:3072
	s_add_u32 s22, s10, 0x800000
	s_addc_u32 s23, s11, 0
	s_add_u32 s24, s12, 0x1000000
	s_addc_u32 s25, s13, 0
	global_load_dwordx2 v[52:53], v245, s[22:23] offset:0
	global_load_dwordx2 v[54:55], v245, s[22:23] offset:512
	global_load_dwordx2 v[56:57], v245, s[22:23] offset:1024
	global_load_dwordx2 v[58:59], v245, s[22:23] offset:1536
	global_load_dwordx4 v[60:63], v244, s[24:25] offset:0
	global_load_dwordx4 v[64:67], v244, s[24:25] offset:1024
	global_load_dwordx4 v[68:71], v244, s[24:25] offset:2048
	global_load_dwordx4 v[72:75], v244, s[24:25] offset:3072
	s_add_u32 s22, s10, 0xc00000
	s_addc_u32 s23, s11, 0
	s_add_u32 s24, s12, 0x1800000
	s_addc_u32 s25, s13, 0
	global_load_dwordx2 v[76:77], v245, s[22:23] offset:0
	global_load_dwordx2 v[78:79], v245, s[22:23] offset:512
	global_load_dwordx2 v[80:81], v245, s[22:23] offset:1024
	global_load_dwordx2 v[82:83], v245, s[22:23] offset:1536
	global_load_dwordx4 v[84:87], v244, s[24:25] offset:0
	global_load_dwordx4 v[88:91], v244, s[24:25] offset:1024
	global_load_dwordx4 v[92:95], v244, s[24:25] offset:2048
	global_load_dwordx4 v[96:99], v244, s[24:25] offset:3072
	s_add_u32 s22, s10, 0x1000000
	s_addc_u32 s23, s11, 0
	s_add_u32 s24, s12, 0x2000000
	s_addc_u32 s25, s13, 0
	global_load_dwordx2 v[100:101], v245, s[22:23] offset:0
	global_load_dwordx2 v[102:103], v245, s[22:23] offset:512
	global_load_dwordx2 v[104:105], v245, s[22:23] offset:1024
	global_load_dwordx2 v[106:107], v245, s[22:23] offset:1536
	global_load_dwordx4 v[108:111], v244, s[24:25] offset:0
	global_load_dwordx4 v[112:115], v244, s[24:25] offset:1024
	global_load_dwordx4 v[116:119], v244, s[24:25] offset:2048
	global_load_dwordx4 v[120:123], v244, s[24:25] offset:3072
	s_add_u32 s22, s10, 0x1400000
	s_addc_u32 s23, s11, 0
	s_add_u32 s24, s12, 0x2800000
	s_addc_u32 s25, s13, 0
	global_load_dwordx2 v[124:125], v245, s[22:23] offset:0
	global_load_dwordx2 v[126:127], v245, s[22:23] offset:512
	global_load_dwordx2 v[128:129], v245, s[22:23] offset:1024
	global_load_dwordx2 v[130:131], v245, s[22:23] offset:1536
	global_load_dwordx4 v[132:135], v244, s[24:25] offset:0
	global_load_dwordx4 v[136:139], v244, s[24:25] offset:1024
	global_load_dwordx4 v[140:143], v244, s[24:25] offset:2048
	global_load_dwordx4 v[144:147], v244, s[24:25] offset:3072
	s_waitcnt vmcnt(40)
	v_lshlrev_b32_e32 v148, 16, v4
	v_and_b32_e32 v149, 0xffff0000, v4
	v_lshlrev_b32_e32 v150, 16, v5
	v_and_b32_e32 v151, 0xffff0000, v5
	v_lshlrev_b32_e32 v152, 16, v6
	v_and_b32_e32 v153, 0xffff0000, v6
	v_lshlrev_b32_e32 v154, 16, v7
	v_and_b32_e32 v155, 0xffff0000, v7
	v_lshlrev_b32_e32 v156, 16, v8
	v_and_b32_e32 v157, 0xffff0000, v8
	v_lshlrev_b32_e32 v158, 16, v9
	v_and_b32_e32 v159, 0xffff0000, v9
	v_lshlrev_b32_e32 v160, 16, v10
	v_and_b32_e32 v161, 0xffff0000, v10
	v_lshlrev_b32_e32 v162, 16, v11
	v_and_b32_e32 v163, 0xffff0000, v11
	s_waitcnt vmcnt(32)
	v_lshlrev_b32_e32 v164, 16, v28
	v_and_b32_e32 v165, 0xffff0000, v28
	v_lshlrev_b32_e32 v166, 16, v29
	v_and_b32_e32 v167, 0xffff0000, v29
	v_lshlrev_b32_e32 v168, 16, v30
	v_and_b32_e32 v169, 0xffff0000, v30
	v_lshlrev_b32_e32 v170, 16, v31
	v_and_b32_e32 v171, 0xffff0000, v31
	v_lshlrev_b32_e32 v172, 16, v32
	v_and_b32_e32 v173, 0xffff0000, v32
	v_lshlrev_b32_e32 v174, 16, v33
	v_and_b32_e32 v175, 0xffff0000, v33
	v_lshlrev_b32_e32 v176, 16, v34
	v_and_b32_e32 v177, 0xffff0000, v34
	v_lshlrev_b32_e32 v178, 16, v35
	v_and_b32_e32 v179, 0xffff0000, v35
	v_pk_mul_f32 v[236:237], v[148:149], v[148:149]
	v_pk_fma_f32 v[236:237], v[150:151], v[150:151], v[236:237]
	v_pk_fma_f32 v[236:237], v[152:153], v[152:153], v[236:237]
	v_pk_fma_f32 v[236:237], v[154:155], v[154:155], v[236:237]
	v_pk_fma_f32 v[236:237], v[156:157], v[156:157], v[236:237]
	v_pk_fma_f32 v[236:237], v[158:159], v[158:159], v[236:237]
	v_pk_fma_f32 v[236:237], v[160:161], v[160:161], v[236:237]
	v_pk_fma_f32 v[236:237], v[162:163], v[162:163], v[236:237]
	v_pk_mul_f32 v[238:239], v[164:165], v[164:165]
	v_pk_fma_f32 v[238:239], v[166:167], v[166:167], v[238:239]
	v_pk_fma_f32 v[238:239], v[168:169], v[168:169], v[238:239]
	v_pk_fma_f32 v[238:239], v[170:171], v[170:171], v[238:239]
	v_pk_fma_f32 v[238:239], v[172:173], v[172:173], v[238:239]
	v_pk_fma_f32 v[238:239], v[174:175], v[174:175], v[238:239]
	v_pk_fma_f32 v[238:239], v[176:177], v[176:177], v[238:239]
	v_pk_fma_f32 v[238:239], v[178:179], v[178:179], v[238:239]
	v_add_f32_e32 v236, v236, v237
	v_add_f32_e32 v238, v238, v239
	s_nop 1
	v_add_f32_dpp v236, v236, v236 quad_perm:[1,0,3,2] row_mask:0xf bank_mask:0xf
	v_add_f32_dpp v238, v238, v238 quad_perm:[1,0,3,2] row_mask:0xf bank_mask:0xf
	s_nop 1
	v_add_f32_dpp v236, v236, v236 quad_perm:[2,3,0,1] row_mask:0xf bank_mask:0xf
	v_add_f32_dpp v238, v238, v238 quad_perm:[2,3,0,1] row_mask:0xf bank_mask:0xf
	s_nop 1
	v_add_f32_dpp v236, v236, v236 row_half_mirror row_mask:0xf bank_mask:0xf
	v_add_f32_dpp v238, v238, v238 row_half_mirror row_mask:0xf bank_mask:0xf
	s_nop 1
	v_add_f32_dpp v236, v236, v236 row_mirror row_mask:0xf bank_mask:0xf
	v_add_f32_dpp v238, v238, v238 row_mirror row_mask:0xf bank_mask:0xf
	s_nop 1
	v_add_f32_dpp v236, v236, v236 row_bcast:15 row_mask:0xa bank_mask:0xf
	v_add_f32_dpp v238, v238, v238 row_bcast:15 row_mask:0xa bank_mask:0xf
	s_nop 1
	v_add_f32_dpp v236, v236, v236 row_bcast:31 row_mask:0xc bank_mask:0xf
	v_add_f32_dpp v238, v238, v238 row_bcast:31 row_mask:0xc bank_mask:0xf
	s_nop 1
	v_readlane_b32 s2, v236, 63
	v_readlane_b32 s3, v238, 63
	s_nop 1
	v_mov_b32_e32 v240, s2
	v_mov_b32_e32 v242, s3
	v_fmamk_f32 v240, v240, 0x3a800000, v196
	v_fmamk_f32 v242, v242, 0x3a800000, v196
	v_rsq_f32_e32 v240, v240
	v_rsq_f32_e32 v242, v242
	s_nop 0
	v_pk_mul_f32 v[148:149], v[148:149], v[240:241] op_sel_hi:[1,0]
	v_pk_mul_f32 v[150:151], v[150:151], v[240:241] op_sel_hi:[1,0]
	v_pk_mul_f32 v[152:153], v[152:153], v[240:241] op_sel_hi:[1,0]
	v_pk_mul_f32 v[154:155], v[154:155], v[240:241] op_sel_hi:[1,0]
	v_pk_mul_f32 v[156:157], v[156:157], v[240:241] op_sel_hi:[1,0]
	v_pk_mul_f32 v[158:159], v[158:159], v[240:241] op_sel_hi:[1,0]
	v_pk_mul_f32 v[160:161], v[160:161], v[240:241] op_sel_hi:[1,0]
	v_pk_mul_f32 v[162:163], v[162:163], v[240:241] op_sel_hi:[1,0]
	v_pk_fma_f32 v[148:149], v[148:149], v[180:181], v[12:13]
	v_pk_fma_f32 v[150:151], v[150:151], v[182:183], v[14:15]
	v_pk_fma_f32 v[152:153], v[152:153], v[184:185], v[16:17]
	v_pk_fma_f32 v[154:155], v[154:155], v[186:187], v[18:19]
	v_pk_fma_f32 v[156:157], v[156:157], v[188:189], v[20:21]
	v_pk_fma_f32 v[158:159], v[158:159], v[190:191], v[22:23]
	v_pk_fma_f32 v[160:161], v[160:161], v[192:193], v[24:25]
	v_pk_fma_f32 v[162:163], v[162:163], v[194:195], v[26:27]
	v_pk_mul_f32 v[164:165], v[164:165], v[242:243] op_sel_hi:[1,0]
	v_pk_mul_f32 v[166:167], v[166:167], v[242:243] op_sel_hi:[1,0]
	v_pk_mul_f32 v[168:169], v[168:169], v[242:243] op_sel_hi:[1,0]
	v_pk_mul_f32 v[170:171], v[170:171], v[242:243] op_sel_hi:[1,0]
	v_pk_mul_f32 v[172:173], v[172:173], v[242:243] op_sel_hi:[1,0]
	v_pk_mul_f32 v[174:175], v[174:175], v[242:243] op_sel_hi:[1,0]
	v_pk_mul_f32 v[176:177], v[176:177], v[242:243] op_sel_hi:[1,0]
	v_pk_mul_f32 v[178:179], v[178:179], v[242:243] op_sel_hi:[1,0]
	v_pk_fma_f32 v[164:165], v[164:165], v[180:181], v[36:37]
	v_pk_fma_f32 v[166:167], v[166:167], v[182:183], v[38:39]
	v_pk_fma_f32 v[168:169], v[168:169], v[184:185], v[40:41]
	v_pk_fma_f32 v[170:171], v[170:171], v[186:187], v[42:43]
	v_pk_fma_f32 v[172:173], v[172:173], v[188:189], v[44:45]
	v_pk_fma_f32 v[174:175], v[174:175], v[190:191], v[46:47]
	v_pk_fma_f32 v[176:177], v[176:177], v[192:193], v[48:49]
	v_pk_fma_f32 v[178:179], v[178:179], v[194:195], v[50:51]
	v_pk_mul_f32 v[236:237], v[148:149], v[148:149]
	v_pk_fma_f32 v[236:237], v[150:151], v[150:151], v[236:237]
	v_pk_fma_f32 v[236:237], v[152:153], v[152:153], v[236:237]
	v_pk_fma_f32 v[236:237], v[154:155], v[154:155], v[236:237]
	v_pk_fma_f32 v[236:237], v[156:157], v[156:157], v[236:237]
	v_pk_fma_f32 v[236:237], v[158:159], v[158:159], v[236:237]
	v_pk_fma_f32 v[236:237], v[160:161], v[160:161], v[236:237]
	v_pk_fma_f32 v[236:237], v[162:163], v[162:163], v[236:237]
	v_pk_mul_f32 v[238:239], v[164:165], v[164:165]
	v_pk_fma_f32 v[238:239], v[166:167], v[166:167], v[238:239]
	v_pk_fma_f32 v[238:239], v[168:169], v[168:169], v[238:239]
	v_pk_fma_f32 v[238:239], v[170:171], v[170:171], v[238:239]
	v_pk_fma_f32 v[238:239], v[172:173], v[172:173], v[238:239]
	v_pk_fma_f32 v[238:239], v[174:175], v[174:175], v[238:239]
	v_pk_fma_f32 v[238:239], v[176:177], v[176:177], v[238:239]
	v_pk_fma_f32 v[238:239], v[178:179], v[178:179], v[238:239]
	v_add_f32_e32 v236, v236, v237
	v_add_f32_e32 v238, v238, v239
	s_nop 1
	v_add_f32_dpp v236, v236, v236 quad_perm:[1,0,3,2] row_mask:0xf bank_mask:0xf
	v_add_f32_dpp v238, v238, v238 quad_perm:[1,0,3,2] row_mask:0xf bank_mask:0xf
	s_nop 1
	v_add_f32_dpp v236, v236, v236 quad_perm:[2,3,0,1] row_mask:0xf bank_mask:0xf
	v_add_f32_dpp v238, v238, v238 quad_perm:[2,3,0,1] row_mask:0xf bank_mask:0xf
	s_nop 1
	v_add_f32_dpp v236, v236, v236 row_half_mirror row_mask:0xf bank_mask:0xf
	v_add_f32_dpp v238, v238, v238 row_half_mirror row_mask:0xf bank_mask:0xf
	s_nop 1
	v_add_f32_dpp v236, v236, v236 row_mirror row_mask:0xf bank_mask:0xf
	v_add_f32_dpp v238, v238, v238 row_mirror row_mask:0xf bank_mask:0xf
	s_nop 1
	v_add_f32_dpp v236, v236, v236 row_bcast:15 row_mask:0xa bank_mask:0xf
	v_add_f32_dpp v238, v238, v238 row_bcast:15 row_mask:0xa bank_mask:0xf
	s_nop 1
	v_add_f32_dpp v236, v236, v236 row_bcast:31 row_mask:0xc bank_mask:0xf
	v_add_f32_dpp v238, v238, v238 row_bcast:31 row_mask:0xc bank_mask:0xf
	s_nop 1
	v_readlane_b32 s2, v236, 63
	v_readlane_b32 s3, v238, 63
	s_nop 1
	v_mov_b32_e32 v240, s2
	v_mov_b32_e32 v242, s3
	v_fmamk_f32 v240, v240, 0x3a800000, v196
	v_fmamk_f32 v242, v242, 0x3a800000, v196
	v_rsq_f32_e32 v240, v240
	v_rsq_f32_e32 v242, v242
	s_nop 0
	v_pk_mul_f32 v[148:149], v[148:149], v[240:241] op_sel_hi:[1,0]
	v_pk_mul_f32 v[150:151], v[150:151], v[240:241] op_sel_hi:[1,0]
	v_pk_mul_f32 v[152:153], v[152:153], v[240:241] op_sel_hi:[1,0]
	v_pk_mul_f32 v[154:155], v[154:155], v[240:241] op_sel_hi:[1,0]
	v_pk_mul_f32 v[156:157], v[156:157], v[240:241] op_sel_hi:[1,0]
	v_pk_mul_f32 v[158:159], v[158:159], v[240:241] op_sel_hi:[1,0]
	v_pk_mul_f32 v[160:161], v[160:161], v[240:241] op_sel_hi:[1,0]
	v_pk_mul_f32 v[162:163], v[162:163], v[240:241] op_sel_hi:[1,0]
	v_pk_mul_f32 v[148:149], v[148:149], v[202:203]
	v_pk_mul_f32 v[150:151], v[150:151], v[204:205]
	v_pk_mul_f32 v[152:153], v[152:153], v[206:207]
	v_pk_mul_f32 v[154:155], v[154:155], v[208:209]
	v_pk_mul_f32 v[156:157], v[156:157], v[210:211]
	v_pk_mul_f32 v[158:159], v[158:159], v[212:213]
	v_pk_mul_f32 v[160:161], v[160:161], v[214:215]
	v_pk_mul_f32 v[162:163], v[162:163], v[216:217]
	v_cvt_pk_bf16_f32 v148, v148, v149
	v_cvt_pk_bf16_f32 v149, v150, v151
	v_cvt_pk_bf16_f32 v150, v152, v153
	v_cvt_pk_bf16_f32 v151, v154, v155
	v_cvt_pk_bf16_f32 v152, v156, v157
	v_cvt_pk_bf16_f32 v153, v158, v159
	v_cvt_pk_bf16_f32 v154, v160, v161
	v_cvt_pk_bf16_f32 v155, v162, v163
	s_mov_b64 s[26:27], s[14:15]
	global_store_dwordx2 v245, v[148:149], s[26:27] offset:0
	global_store_dwordx2 v245, v[150:151], s[26:27] offset:512
	global_store_dwordx2 v245, v[152:153], s[26:27] offset:1024
	global_store_dwordx2 v245, v[154:155], s[26:27] offset:1536
	v_pk_mul_f32 v[164:165], v[164:165], v[242:243] op_sel_hi:[1,0]
	v_pk_mul_f32 v[166:167], v[166:167], v[242:243] op_sel_hi:[1,0]
	v_pk_mul_f32 v[168:169], v[168:169], v[242:243] op_sel_hi:[1,0]
	v_pk_mul_f32 v[170:171], v[170:171], v[242:243] op_sel_hi:[1,0]
	v_pk_mul_f32 v[172:173], v[172:173], v[242:243] op_sel_hi:[1,0]
	v_pk_mul_f32 v[174:175], v[174:175], v[242:243] op_sel_hi:[1,0]
	v_pk_mul_f32 v[176:177], v[176:177], v[242:243] op_sel_hi:[1,0]
	v_pk_mul_f32 v[178:179], v[178:179], v[242:243] op_sel_hi:[1,0]
	v_pk_mul_f32 v[164:165], v[164:165], v[202:203]
	v_pk_mul_f32 v[166:167], v[166:167], v[204:205]
	v_pk_mul_f32 v[168:169], v[168:169], v[206:207]
	v_pk_mul_f32 v[170:171], v[170:171], v[208:209]
	v_pk_mul_f32 v[172:173], v[172:173], v[210:211]
	v_pk_mul_f32 v[174:175], v[174:175], v[212:213]
	v_pk_mul_f32 v[176:177], v[176:177], v[214:215]
	v_pk_mul_f32 v[178:179], v[178:179], v[216:217]
	v_cvt_pk_bf16_f32 v164, v164, v165
	v_cvt_pk_bf16_f32 v165, v166, v167
	v_cvt_pk_bf16_f32 v166, v168, v169
	v_cvt_pk_bf16_f32 v167, v170, v171
	v_cvt_pk_bf16_f32 v168, v172, v173
	v_cvt_pk_bf16_f32 v169, v174, v175
	v_cvt_pk_bf16_f32 v170, v176, v177
	v_cvt_pk_bf16_f32 v171, v178, v179
	s_add_u32 s26, s14, 0x400000
	s_addc_u32 s27, s15, 0
	global_store_dwordx2 v245, v[164:165], s[26:27] offset:0
	global_store_dwordx2 v245, v[166:167], s[26:27] offset:512
	global_store_dwordx2 v245, v[168:169], s[26:27] offset:1024
	global_store_dwordx2 v245, v[170:171], s[26:27] offset:1536
	s_add_u32 s22, s10, 0x1800000
	s_addc_u32 s23, s11, 0
	s_add_u32 s24, s12, 0x3000000
	s_addc_u32 s25, s13, 0
	global_load_dwordx2 v[4:5], v245, s[22:23] offset:0
	global_load_dwordx2 v[6:7], v245, s[22:23] offset:512
	global_load_dwordx2 v[8:9], v245, s[22:23] offset:1024
	global_load_dwordx2 v[10:11], v245, s[22:23] offset:1536
	global_load_dwordx4 v[12:15], v244, s[24:25] offset:0
	global_load_dwordx4 v[16:19], v244, s[24:25] offset:1024
	global_load_dwordx4 v[20:23], v244, s[24:25] offset:2048
	global_load_dwordx4 v[24:27], v244, s[24:25] offset:3072
	s_add_u32 s22, s10, 0x1c00000
	s_addc_u32 s23, s11, 0
	s_add_u32 s24, s12, 0x3800000
	s_addc_u32 s25, s13, 0
	global_load_dwordx2 v[28:29], v245, s[22:23] offset:0
	global_load_dwordx2 v[30:31], v245, s[22:23] offset:512
	global_load_dwordx2 v[32:33], v245, s[22:23] offset:1024
	global_load_dwordx2 v[34:35], v245, s[22:23] offset:1536
	global_load_dwordx4 v[36:39], v244, s[24:25] offset:0
	global_load_dwordx4 v[40:43], v244, s[24:25] offset:1024
	global_load_dwordx4 v[44:47], v244, s[24:25] offset:2048
	global_load_dwordx4 v[48:51], v244, s[24:25] offset:3072
	s_waitcnt vmcnt(48)
	v_lshlrev_b32_e32 v148, 16, v52
	v_and_b32_e32 v149, 0xffff0000, v52
	v_lshlrev_b32_e32 v150, 16, v53
	v_and_b32_e32 v151, 0xffff0000, v53
	v_lshlrev_b32_e32 v152, 16, v54
	v_and_b32_e32 v153, 0xffff0000, v54
	v_lshlrev_b32_e32 v154, 16, v55
	v_and_b32_e32 v155, 0xffff0000, v55
	v_lshlrev_b32_e32 v156, 16, v56
	v_and_b32_e32 v157, 0xffff0000, v56
	v_lshlrev_b32_e32 v158, 16, v57
	v_and_b32_e32 v159, 0xffff0000, v57
	v_lshlrev_b32_e32 v160, 16, v58
	v_and_b32_e32 v161, 0xffff0000, v58
	v_lshlrev_b32_e32 v162, 16, v59
	v_and_b32_e32 v163, 0xffff0000, v59
	s_waitcnt vmcnt(40)
	v_lshlrev_b32_e32 v164, 16, v76
	v_and_b32_e32 v165, 0xffff0000, v76
	v_lshlrev_b32_e32 v166, 16, v77
	v_and_b32_e32 v167, 0xffff0000, v77
	v_lshlrev_b32_e32 v168, 16, v78
	v_and_b32_e32 v169, 0xffff0000, v78
	v_lshlrev_b32_e32 v170, 16, v79
	v_and_b32_e32 v171, 0xffff0000, v79
	v_lshlrev_b32_e32 v172, 16, v80
	v_and_b32_e32 v173, 0xffff0000, v80
	v_lshlrev_b32_e32 v174, 16, v81
	v_and_b32_e32 v175, 0xffff0000, v81
	v_lshlrev_b32_e32 v176, 16, v82
	v_and_b32_e32 v177, 0xffff0000, v82
	v_lshlrev_b32_e32 v178, 16, v83
	v_and_b32_e32 v179, 0xffff0000, v83
	v_pk_mul_f32 v[236:237], v[148:149], v[148:149]
	v_pk_fma_f32 v[236:237], v[150:151], v[150:151], v[236:237]
	v_pk_fma_f32 v[236:237], v[152:153], v[152:153], v[236:237]
	v_pk_fma_f32 v[236:237], v[154:155], v[154:155], v[236:237]
	v_pk_fma_f32 v[236:237], v[156:157], v[156:157], v[236:237]
	v_pk_fma_f32 v[236:237], v[158:159], v[158:159], v[236:237]
	v_pk_fma_f32 v[236:237], v[160:161], v[160:161], v[236:237]
	v_pk_fma_f32 v[236:237], v[162:163], v[162:163], v[236:237]
	v_pk_mul_f32 v[238:239], v[164:165], v[164:165]
	v_pk_fma_f32 v[238:239], v[166:167], v[166:167], v[238:239]
	v_pk_fma_f32 v[238:239], v[168:169], v[168:169], v[238:239]
	v_pk_fma_f32 v[238:239], v[170:171], v[170:171], v[238:239]
	v_pk_fma_f32 v[238:239], v[172:173], v[172:173], v[238:239]
	v_pk_fma_f32 v[238:239], v[174:175], v[174:175], v[238:239]
	v_pk_fma_f32 v[238:239], v[176:177], v[176:177], v[238:239]
	v_pk_fma_f32 v[238:239], v[178:179], v[178:179], v[238:239]
	v_add_f32_e32 v236, v236, v237
	v_add_f32_e32 v238, v238, v239
	s_nop 1
	v_add_f32_dpp v236, v236, v236 quad_perm:[1,0,3,2] row_mask:0xf bank_mask:0xf
	v_add_f32_dpp v238, v238, v238 quad_perm:[1,0,3,2] row_mask:0xf bank_mask:0xf
	s_nop 1
	v_add_f32_dpp v236, v236, v236 quad_perm:[2,3,0,1] row_mask:0xf bank_mask:0xf
	v_add_f32_dpp v238, v238, v238 quad_perm:[2,3,0,1] row_mask:0xf bank_mask:0xf
	s_nop 1
	v_add_f32_dpp v236, v236, v236 row_half_mirror row_mask:0xf bank_mask:0xf
	v_add_f32_dpp v238, v238, v238 row_half_mirror row_mask:0xf bank_mask:0xf
	s_nop 1
	v_add_f32_dpp v236, v236, v236 row_mirror row_mask:0xf bank_mask:0xf
	v_add_f32_dpp v238, v238, v238 row_mirror row_mask:0xf bank_mask:0xf
	s_nop 1
	v_add_f32_dpp v236, v236, v236 row_bcast:15 row_mask:0xa bank_mask:0xf
	v_add_f32_dpp v238, v238, v238 row_bcast:15 row_mask:0xa bank_mask:0xf
	s_nop 1
	v_add_f32_dpp v236, v236, v236 row_bcast:31 row_mask:0xc bank_mask:0xf
	v_add_f32_dpp v238, v238, v238 row_bcast:31 row_mask:0xc bank_mask:0xf
	s_nop 1
	v_readlane_b32 s2, v236, 63
	v_readlane_b32 s3, v238, 63
	s_nop 1
	v_mov_b32_e32 v240, s2
	v_mov_b32_e32 v242, s3
	v_fmamk_f32 v240, v240, 0x3a800000, v196
	v_fmamk_f32 v242, v242, 0x3a800000, v196
	v_rsq_f32_e32 v240, v240
	v_rsq_f32_e32 v242, v242
	s_nop 0
	v_pk_mul_f32 v[148:149], v[148:149], v[240:241] op_sel_hi:[1,0]
	v_pk_mul_f32 v[150:151], v[150:151], v[240:241] op_sel_hi:[1,0]
	v_pk_mul_f32 v[152:153], v[152:153], v[240:241] op_sel_hi:[1,0]
	v_pk_mul_f32 v[154:155], v[154:155], v[240:241] op_sel_hi:[1,0]
	v_pk_mul_f32 v[156:157], v[156:157], v[240:241] op_sel_hi:[1,0]
	v_pk_mul_f32 v[158:159], v[158:159], v[240:241] op_sel_hi:[1,0]
	v_pk_mul_f32 v[160:161], v[160:161], v[240:241] op_sel_hi:[1,0]
	v_pk_mul_f32 v[162:163], v[162:163], v[240:241] op_sel_hi:[1,0]
	v_pk_fma_f32 v[148:149], v[148:149], v[180:181], v[60:61]
	v_pk_fma_f32 v[150:151], v[150:151], v[182:183], v[62:63]
	v_pk_fma_f32 v[152:153], v[152:153], v[184:185], v[64:65]
	v_pk_fma_f32 v[154:155], v[154:155], v[186:187], v[66:67]
	v_pk_fma_f32 v[156:157], v[156:157], v[188:189], v[68:69]
	v_pk_fma_f32 v[158:159], v[158:159], v[190:191], v[70:71]
	v_pk_fma_f32 v[160:161], v[160:161], v[192:193], v[72:73]
	v_pk_fma_f32 v[162:163], v[162:163], v[194:195], v[74:75]
	v_pk_mul_f32 v[164:165], v[164:165], v[242:243] op_sel_hi:[1,0]
	v_pk_mul_f32 v[166:167], v[166:167], v[242:243] op_sel_hi:[1,0]
	v_pk_mul_f32 v[168:169], v[168:169], v[242:243] op_sel_hi:[1,0]
	v_pk_mul_f32 v[170:171], v[170:171], v[242:243] op_sel_hi:[1,0]
	v_pk_mul_f32 v[172:173], v[172:173], v[242:243] op_sel_hi:[1,0]
	v_pk_mul_f32 v[174:175], v[174:175], v[242:243] op_sel_hi:[1,0]
	v_pk_mul_f32 v[176:177], v[176:177], v[242:243] op_sel_hi:[1,0]
	v_pk_mul_f32 v[178:179], v[178:179], v[242:243] op_sel_hi:[1,0]
	v_pk_fma_f32 v[164:165], v[164:165], v[180:181], v[84:85]
	v_pk_fma_f32 v[166:167], v[166:167], v[182:183], v[86:87]
	v_pk_fma_f32 v[168:169], v[168:169], v[184:185], v[88:89]
	v_pk_fma_f32 v[170:171], v[170:171], v[186:187], v[90:91]
	v_pk_fma_f32 v[172:173], v[172:173], v[188:189], v[92:93]
	v_pk_fma_f32 v[174:175], v[174:175], v[190:191], v[94:95]
	v_pk_fma_f32 v[176:177], v[176:177], v[192:193], v[96:97]
	v_pk_fma_f32 v[178:179], v[178:179], v[194:195], v[98:99]
	v_pk_mul_f32 v[236:237], v[148:149], v[148:149]
	v_pk_fma_f32 v[236:237], v[150:151], v[150:151], v[236:237]
	v_pk_fma_f32 v[236:237], v[152:153], v[152:153], v[236:237]
	v_pk_fma_f32 v[236:237], v[154:155], v[154:155], v[236:237]
	v_pk_fma_f32 v[236:237], v[156:157], v[156:157], v[236:237]
	v_pk_fma_f32 v[236:237], v[158:159], v[158:159], v[236:237]
	v_pk_fma_f32 v[236:237], v[160:161], v[160:161], v[236:237]
	v_pk_fma_f32 v[236:237], v[162:163], v[162:163], v[236:237]
	v_pk_mul_f32 v[238:239], v[164:165], v[164:165]
	v_pk_fma_f32 v[238:239], v[166:167], v[166:167], v[238:239]
	v_pk_fma_f32 v[238:239], v[168:169], v[168:169], v[238:239]
	v_pk_fma_f32 v[238:239], v[170:171], v[170:171], v[238:239]
	v_pk_fma_f32 v[238:239], v[172:173], v[172:173], v[238:239]
	v_pk_fma_f32 v[238:239], v[174:175], v[174:175], v[238:239]
	v_pk_fma_f32 v[238:239], v[176:177], v[176:177], v[238:239]
	v_pk_fma_f32 v[238:239], v[178:179], v[178:179], v[238:239]
	v_add_f32_e32 v236, v236, v237
	v_add_f32_e32 v238, v238, v239
	s_nop 1
	v_add_f32_dpp v236, v236, v236 quad_perm:[1,0,3,2] row_mask:0xf bank_mask:0xf
	v_add_f32_dpp v238, v238, v238 quad_perm:[1,0,3,2] row_mask:0xf bank_mask:0xf
	s_nop 1
	v_add_f32_dpp v236, v236, v236 quad_perm:[2,3,0,1] row_mask:0xf bank_mask:0xf
	v_add_f32_dpp v238, v238, v238 quad_perm:[2,3,0,1] row_mask:0xf bank_mask:0xf
	s_nop 1
	v_add_f32_dpp v236, v236, v236 row_half_mirror row_mask:0xf bank_mask:0xf
	v_add_f32_dpp v238, v238, v238 row_half_mirror row_mask:0xf bank_mask:0xf
	s_nop 1
	v_add_f32_dpp v236, v236, v236 row_mirror row_mask:0xf bank_mask:0xf
	v_add_f32_dpp v238, v238, v238 row_mirror row_mask:0xf bank_mask:0xf
	s_nop 1
	v_add_f32_dpp v236, v236, v236 row_bcast:15 row_mask:0xa bank_mask:0xf
	v_add_f32_dpp v238, v238, v238 row_bcast:15 row_mask:0xa bank_mask:0xf
	s_nop 1
	v_add_f32_dpp v236, v236, v236 row_bcast:31 row_mask:0xc bank_mask:0xf
	v_add_f32_dpp v238, v238, v238 row_bcast:31 row_mask:0xc bank_mask:0xf
	s_nop 1
	v_readlane_b32 s2, v236, 63
	v_readlane_b32 s3, v238, 63
	s_nop 1
	v_mov_b32_e32 v240, s2
	v_mov_b32_e32 v242, s3
	v_fmamk_f32 v240, v240, 0x3a800000, v196
	v_fmamk_f32 v242, v242, 0x3a800000, v196
	v_rsq_f32_e32 v240, v240
	v_rsq_f32_e32 v242, v242
	s_nop 0
	v_pk_mul_f32 v[148:149], v[148:149], v[240:241] op_sel_hi:[1,0]
	v_pk_mul_f32 v[150:151], v[150:151], v[240:241] op_sel_hi:[1,0]
	v_pk_mul_f32 v[152:153], v[152:153], v[240:241] op_sel_hi:[1,0]
	v_pk_mul_f32 v[154:155], v[154:155], v[240:241] op_sel_hi:[1,0]
	v_pk_mul_f32 v[156:157], v[156:157], v[240:241] op_sel_hi:[1,0]
	v_pk_mul_f32 v[158:159], v[158:159], v[240:241] op_sel_hi:[1,0]
	v_pk_mul_f32 v[160:161], v[160:161], v[240:241] op_sel_hi:[1,0]
	v_pk_mul_f32 v[162:163], v[162:163], v[240:241] op_sel_hi:[1,0]
	v_pk_mul_f32 v[148:149], v[148:149], v[202:203]
	v_pk_mul_f32 v[150:151], v[150:151], v[204:205]
	v_pk_mul_f32 v[152:153], v[152:153], v[206:207]
	v_pk_mul_f32 v[154:155], v[154:155], v[208:209]
	v_pk_mul_f32 v[156:157], v[156:157], v[210:211]
	v_pk_mul_f32 v[158:159], v[158:159], v[212:213]
	v_pk_mul_f32 v[160:161], v[160:161], v[214:215]
	v_pk_mul_f32 v[162:163], v[162:163], v[216:217]
	v_cvt_pk_bf16_f32 v148, v148, v149
	v_cvt_pk_bf16_f32 v149, v150, v151
	v_cvt_pk_bf16_f32 v150, v152, v153
	v_cvt_pk_bf16_f32 v151, v154, v155
	v_cvt_pk_bf16_f32 v152, v156, v157
	v_cvt_pk_bf16_f32 v153, v158, v159
	v_cvt_pk_bf16_f32 v154, v160, v161
	v_cvt_pk_bf16_f32 v155, v162, v163
	s_add_u32 s26, s14, 0x800000
	s_addc_u32 s27, s15, 0
	global_store_dwordx2 v245, v[148:149], s[26:27] offset:0
	global_store_dwordx2 v245, v[150:151], s[26:27] offset:512
	global_store_dwordx2 v245, v[152:153], s[26:27] offset:1024
	global_store_dwordx2 v245, v[154:155], s[26:27] offset:1536
	v_pk_mul_f32 v[164:165], v[164:165], v[242:243] op_sel_hi:[1,0]
	v_pk_mul_f32 v[166:167], v[166:167], v[242:243] op_sel_hi:[1,0]
	v_pk_mul_f32 v[168:169], v[168:169], v[242:243] op_sel_hi:[1,0]
	v_pk_mul_f32 v[170:171], v[170:171], v[242:243] op_sel_hi:[1,0]
	v_pk_mul_f32 v[172:173], v[172:173], v[242:243] op_sel_hi:[1,0]
	v_pk_mul_f32 v[174:175], v[174:175], v[242:243] op_sel_hi:[1,0]
	v_pk_mul_f32 v[176:177], v[176:177], v[242:243] op_sel_hi:[1,0]
	v_pk_mul_f32 v[178:179], v[178:179], v[242:243] op_sel_hi:[1,0]
	v_pk_mul_f32 v[164:165], v[164:165], v[202:203]
	v_pk_mul_f32 v[166:167], v[166:167], v[204:205]
	v_pk_mul_f32 v[168:169], v[168:169], v[206:207]
	v_pk_mul_f32 v[170:171], v[170:171], v[208:209]
	v_pk_mul_f32 v[172:173], v[172:173], v[210:211]
	v_pk_mul_f32 v[174:175], v[174:175], v[212:213]
	v_pk_mul_f32 v[176:177], v[176:177], v[214:215]
	v_pk_mul_f32 v[178:179], v[178:179], v[216:217]
	v_cvt_pk_bf16_f32 v164, v164, v165
	v_cvt_pk_bf16_f32 v165, v166, v167
	v_cvt_pk_bf16_f32 v166, v168, v169
	v_cvt_pk_bf16_f32 v167, v170, v171
	v_cvt_pk_bf16_f32 v168, v172, v173
	v_cvt_pk_bf16_f32 v169, v174, v175
	v_cvt_pk_bf16_f32 v170, v176, v177
	v_cvt_pk_bf16_f32 v171, v178, v179
	s_add_u32 s26, s14, 0xc00000
	s_addc_u32 s27, s15, 0
	global_store_dwordx2 v245, v[164:165], s[26:27] offset:0
	global_store_dwordx2 v245, v[166:167], s[26:27] offset:512
	global_store_dwordx2 v245, v[168:169], s[26:27] offset:1024
	global_store_dwordx2 v245, v[170:171], s[26:27] offset:1536
	s_add_u32 s22, s10, 0x2000000
	s_addc_u32 s23, s11, 0
	s_add_u32 s24, s12, 0x4000000
	s_addc_u32 s25, s13, 0
	global_load_dwordx2 v[52:53], v245, s[22:23] offset:0
	global_load_dwordx2 v[54:55], v245, s[22:23] offset:512
	global_load_dwordx2 v[56:57], v245, s[22:23] offset:1024
	global_load_dwordx2 v[58:59], v245, s[22:23] offset:1536
	global_load_dwordx4 v[60:63], v244, s[24:25] offset:0
	global_load_dwordx4 v[64:67], v244, s[24:25] offset:1024
	global_load_dwordx4 v[68:71], v244, s[24:25] offset:2048
	global_load_dwordx4 v[72:75], v244, s[24:25] offset:3072
	s_add_u32 s22, s10, 0x2400000
	s_addc_u32 s23, s11, 0
	s_add_u32 s24, s12, 0x4800000
	s_addc_u32 s25, s13, 0
	global_load_dwordx2 v[76:77], v245, s[22:23] offset:0
	global_load_dwordx2 v[78:79], v245, s[22:23] offset:512
	global_load_dwordx2 v[80:81], v245, s[22:23] offset:1024
	global_load_dwordx2 v[82:83], v245, s[22:23] offset:1536
	global_load_dwordx4 v[84:87], v244, s[24:25] offset:0
	global_load_dwordx4 v[88:91], v244, s[24:25] offset:1024
	global_load_dwordx4 v[92:95], v244, s[24:25] offset:2048
	global_load_dwordx4 v[96:99], v244, s[24:25] offset:3072
	s_waitcnt vmcnt(56)
	v_lshlrev_b32_e32 v148, 16, v100
	v_and_b32_e32 v149, 0xffff0000, v100
	v_lshlrev_b32_e32 v150, 16, v101
	v_and_b32_e32 v151, 0xffff0000, v101
	v_lshlrev_b32_e32 v152, 16, v102
	v_and_b32_e32 v153, 0xffff0000, v102
	v_lshlrev_b32_e32 v154, 16, v103
	v_and_b32_e32 v155, 0xffff0000, v103
	v_lshlrev_b32_e32 v156, 16, v104
	v_and_b32_e32 v157, 0xffff0000, v104
	v_lshlrev_b32_e32 v158, 16, v105
	v_and_b32_e32 v159, 0xffff0000, v105
	v_lshlrev_b32_e32 v160, 16, v106
	v_and_b32_e32 v161, 0xffff0000, v106
	v_lshlrev_b32_e32 v162, 16, v107
	v_and_b32_e32 v163, 0xffff0000, v107
	s_waitcnt vmcnt(48)
	v_lshlrev_b32_e32 v164, 16, v124
	v_and_b32_e32 v165, 0xffff0000, v124
	v_lshlrev_b32_e32 v166, 16, v125
	v_and_b32_e32 v167, 0xffff0000, v125
	v_lshlrev_b32_e32 v168, 16, v126
	v_and_b32_e32 v169, 0xffff0000, v126
	v_lshlrev_b32_e32 v170, 16, v127
	v_and_b32_e32 v171, 0xffff0000, v127
	v_lshlrev_b32_e32 v172, 16, v128
	v_and_b32_e32 v173, 0xffff0000, v128
	v_lshlrev_b32_e32 v174, 16, v129
	v_and_b32_e32 v175, 0xffff0000, v129
	v_lshlrev_b32_e32 v176, 16, v130
	v_and_b32_e32 v177, 0xffff0000, v130
	v_lshlrev_b32_e32 v178, 16, v131
	v_and_b32_e32 v179, 0xffff0000, v131
	v_pk_mul_f32 v[236:237], v[148:149], v[148:149]
	v_pk_fma_f32 v[236:237], v[150:151], v[150:151], v[236:237]
	v_pk_fma_f32 v[236:237], v[152:153], v[152:153], v[236:237]
	v_pk_fma_f32 v[236:237], v[154:155], v[154:155], v[236:237]
	v_pk_fma_f32 v[236:237], v[156:157], v[156:157], v[236:237]
	v_pk_fma_f32 v[236:237], v[158:159], v[158:159], v[236:237]
	v_pk_fma_f32 v[236:237], v[160:161], v[160:161], v[236:237]
	v_pk_fma_f32 v[236:237], v[162:163], v[162:163], v[236:237]
	v_pk_mul_f32 v[238:239], v[164:165], v[164:165]
	v_pk_fma_f32 v[238:239], v[166:167], v[166:167], v[238:239]
	v_pk_fma_f32 v[238:239], v[168:169], v[168:169], v[238:239]
	v_pk_fma_f32 v[238:239], v[170:171], v[170:171], v[238:239]
	v_pk_fma_f32 v[238:239], v[172:173], v[172:173], v[238:239]
	v_pk_fma_f32 v[238:239], v[174:175], v[174:175], v[238:239]
	v_pk_fma_f32 v[238:239], v[176:177], v[176:177], v[238:239]
	v_pk_fma_f32 v[238:239], v[178:179], v[178:179], v[238:239]
	v_add_f32_e32 v236, v236, v237
	v_add_f32_e32 v238, v238, v239
	s_nop 1
	v_add_f32_dpp v236, v236, v236 quad_perm:[1,0,3,2] row_mask:0xf bank_mask:0xf
	v_add_f32_dpp v238, v238, v238 quad_perm:[1,0,3,2] row_mask:0xf bank_mask:0xf
	s_nop 1
	v_add_f32_dpp v236, v236, v236 quad_perm:[2,3,0,1] row_mask:0xf bank_mask:0xf
	v_add_f32_dpp v238, v238, v238 quad_perm:[2,3,0,1] row_mask:0xf bank_mask:0xf
	s_nop 1
	v_add_f32_dpp v236, v236, v236 row_half_mirror row_mask:0xf bank_mask:0xf
	v_add_f32_dpp v238, v238, v238 row_half_mirror row_mask:0xf bank_mask:0xf
	s_nop 1
	v_add_f32_dpp v236, v236, v236 row_mirror row_mask:0xf bank_mask:0xf
	v_add_f32_dpp v238, v238, v238 row_mirror row_mask:0xf bank_mask:0xf
	s_nop 1
	v_add_f32_dpp v236, v236, v236 row_bcast:15 row_mask:0xa bank_mask:0xf
	v_add_f32_dpp v238, v238, v238 row_bcast:15 row_mask:0xa bank_mask:0xf
	s_nop 1
	v_add_f32_dpp v236, v236, v236 row_bcast:31 row_mask:0xc bank_mask:0xf
	v_add_f32_dpp v238, v238, v238 row_bcast:31 row_mask:0xc bank_mask:0xf
	s_nop 1
	v_readlane_b32 s2, v236, 63
	v_readlane_b32 s3, v238, 63
	s_nop 1
	v_mov_b32_e32 v240, s2
	v_mov_b32_e32 v242, s3
	v_fmamk_f32 v240, v240, 0x3a800000, v196
	v_fmamk_f32 v242, v242, 0x3a800000, v196
	v_rsq_f32_e32 v240, v240
	v_rsq_f32_e32 v242, v242
	s_nop 0
	v_pk_mul_f32 v[148:149], v[148:149], v[240:241] op_sel_hi:[1,0]
	v_pk_mul_f32 v[150:151], v[150:151], v[240:241] op_sel_hi:[1,0]
	v_pk_mul_f32 v[152:153], v[152:153], v[240:241] op_sel_hi:[1,0]
	v_pk_mul_f32 v[154:155], v[154:155], v[240:241] op_sel_hi:[1,0]
	v_pk_mul_f32 v[156:157], v[156:157], v[240:241] op_sel_hi:[1,0]
	v_pk_mul_f32 v[158:159], v[158:159], v[240:241] op_sel_hi:[1,0]
	v_pk_mul_f32 v[160:161], v[160:161], v[240:241] op_sel_hi:[1,0]
	v_pk_mul_f32 v[162:163], v[162:163], v[240:241] op_sel_hi:[1,0]
	v_pk_fma_f32 v[148:149], v[148:149], v[180:181], v[108:109]
	v_pk_fma_f32 v[150:151], v[150:151], v[182:183], v[110:111]
	v_pk_fma_f32 v[152:153], v[152:153], v[184:185], v[112:113]
	v_pk_fma_f32 v[154:155], v[154:155], v[186:187], v[114:115]
	v_pk_fma_f32 v[156:157], v[156:157], v[188:189], v[116:117]
	v_pk_fma_f32 v[158:159], v[158:159], v[190:191], v[118:119]
	v_pk_fma_f32 v[160:161], v[160:161], v[192:193], v[120:121]
	v_pk_fma_f32 v[162:163], v[162:163], v[194:195], v[122:123]
	v_pk_mul_f32 v[164:165], v[164:165], v[242:243] op_sel_hi:[1,0]
	v_pk_mul_f32 v[166:167], v[166:167], v[242:243] op_sel_hi:[1,0]
	v_pk_mul_f32 v[168:169], v[168:169], v[242:243] op_sel_hi:[1,0]
	v_pk_mul_f32 v[170:171], v[170:171], v[242:243] op_sel_hi:[1,0]
	v_pk_mul_f32 v[172:173], v[172:173], v[242:243] op_sel_hi:[1,0]
	v_pk_mul_f32 v[174:175], v[174:175], v[242:243] op_sel_hi:[1,0]
	v_pk_mul_f32 v[176:177], v[176:177], v[242:243] op_sel_hi:[1,0]
	v_pk_mul_f32 v[178:179], v[178:179], v[242:243] op_sel_hi:[1,0]
	v_pk_fma_f32 v[164:165], v[164:165], v[180:181], v[132:133]
	v_pk_fma_f32 v[166:167], v[166:167], v[182:183], v[134:135]
	v_pk_fma_f32 v[168:169], v[168:169], v[184:185], v[136:137]
	v_pk_fma_f32 v[170:171], v[170:171], v[186:187], v[138:139]
	v_pk_fma_f32 v[172:173], v[172:173], v[188:189], v[140:141]
	v_pk_fma_f32 v[174:175], v[174:175], v[190:191], v[142:143]
	v_pk_fma_f32 v[176:177], v[176:177], v[192:193], v[144:145]
	v_pk_fma_f32 v[178:179], v[178:179], v[194:195], v[146:147]
	v_pk_mul_f32 v[236:237], v[148:149], v[148:149]
	v_pk_fma_f32 v[236:237], v[150:151], v[150:151], v[236:237]
	v_pk_fma_f32 v[236:237], v[152:153], v[152:153], v[236:237]
	v_pk_fma_f32 v[236:237], v[154:155], v[154:155], v[236:237]
	v_pk_fma_f32 v[236:237], v[156:157], v[156:157], v[236:237]
	v_pk_fma_f32 v[236:237], v[158:159], v[158:159], v[236:237]
	v_pk_fma_f32 v[236:237], v[160:161], v[160:161], v[236:237]
	v_pk_fma_f32 v[236:237], v[162:163], v[162:163], v[236:237]
	v_pk_mul_f32 v[238:239], v[164:165], v[164:165]
	v_pk_fma_f32 v[238:239], v[166:167], v[166:167], v[238:239]
	v_pk_fma_f32 v[238:239], v[168:169], v[168:169], v[238:239]
	v_pk_fma_f32 v[238:239], v[170:171], v[170:171], v[238:239]
	v_pk_fma_f32 v[238:239], v[172:173], v[172:173], v[238:239]
	v_pk_fma_f32 v[238:239], v[174:175], v[174:175], v[238:239]
	v_pk_fma_f32 v[238:239], v[176:177], v[176:177], v[238:239]
	v_pk_fma_f32 v[238:239], v[178:179], v[178:179], v[238:239]
	v_add_f32_e32 v236, v236, v237
	v_add_f32_e32 v238, v238, v239
	s_nop 1
	v_add_f32_dpp v236, v236, v236 quad_perm:[1,0,3,2] row_mask:0xf bank_mask:0xf
	v_add_f32_dpp v238, v238, v238 quad_perm:[1,0,3,2] row_mask:0xf bank_mask:0xf
	s_nop 1
	v_add_f32_dpp v236, v236, v236 quad_perm:[2,3,0,1] row_mask:0xf bank_mask:0xf
	v_add_f32_dpp v238, v238, v238 quad_perm:[2,3,0,1] row_mask:0xf bank_mask:0xf
	s_nop 1
	v_add_f32_dpp v236, v236, v236 row_half_mirror row_mask:0xf bank_mask:0xf
	v_add_f32_dpp v238, v238, v238 row_half_mirror row_mask:0xf bank_mask:0xf
	s_nop 1
	v_add_f32_dpp v236, v236, v236 row_mirror row_mask:0xf bank_mask:0xf
	v_add_f32_dpp v238, v238, v238 row_mirror row_mask:0xf bank_mask:0xf
	s_nop 1
	v_add_f32_dpp v236, v236, v236 row_bcast:15 row_mask:0xa bank_mask:0xf
	v_add_f32_dpp v238, v238, v238 row_bcast:15 row_mask:0xa bank_mask:0xf
	s_nop 1
	v_add_f32_dpp v236, v236, v236 row_bcast:31 row_mask:0xc bank_mask:0xf
	v_add_f32_dpp v238, v238, v238 row_bcast:31 row_mask:0xc bank_mask:0xf
	s_nop 1
	v_readlane_b32 s2, v236, 63
	v_readlane_b32 s3, v238, 63
	s_nop 1
	v_mov_b32_e32 v240, s2
	v_mov_b32_e32 v242, s3
	v_fmamk_f32 v240, v240, 0x3a800000, v196
	v_fmamk_f32 v242, v242, 0x3a800000, v196
	v_rsq_f32_e32 v240, v240
	v_rsq_f32_e32 v242, v242
	s_nop 0
	v_pk_mul_f32 v[148:149], v[148:149], v[240:241] op_sel_hi:[1,0]
	v_pk_mul_f32 v[150:151], v[150:151], v[240:241] op_sel_hi:[1,0]
	v_pk_mul_f32 v[152:153], v[152:153], v[240:241] op_sel_hi:[1,0]
	v_pk_mul_f32 v[154:155], v[154:155], v[240:241] op_sel_hi:[1,0]
	v_pk_mul_f32 v[156:157], v[156:157], v[240:241] op_sel_hi:[1,0]
	v_pk_mul_f32 v[158:159], v[158:159], v[240:241] op_sel_hi:[1,0]
	v_pk_mul_f32 v[160:161], v[160:161], v[240:241] op_sel_hi:[1,0]
	v_pk_mul_f32 v[162:163], v[162:163], v[240:241] op_sel_hi:[1,0]
	v_pk_mul_f32 v[148:149], v[148:149], v[202:203]
	v_pk_mul_f32 v[150:151], v[150:151], v[204:205]
	v_pk_mul_f32 v[152:153], v[152:153], v[206:207]
	v_pk_mul_f32 v[154:155], v[154:155], v[208:209]
	v_pk_mul_f32 v[156:157], v[156:157], v[210:211]
	v_pk_mul_f32 v[158:159], v[158:159], v[212:213]
	v_pk_mul_f32 v[160:161], v[160:161], v[214:215]
	v_pk_mul_f32 v[162:163], v[162:163], v[216:217]
	v_cvt_pk_bf16_f32 v148, v148, v149
	v_cvt_pk_bf16_f32 v149, v150, v151
	v_cvt_pk_bf16_f32 v150, v152, v153
	v_cvt_pk_bf16_f32 v151, v154, v155
	v_cvt_pk_bf16_f32 v152, v156, v157
	v_cvt_pk_bf16_f32 v153, v158, v159
	v_cvt_pk_bf16_f32 v154, v160, v161
	v_cvt_pk_bf16_f32 v155, v162, v163
	s_add_u32 s26, s14, 0x1000000
	s_addc_u32 s27, s15, 0
	global_store_dwordx2 v245, v[148:149], s[26:27] offset:0
	global_store_dwordx2 v245, v[150:151], s[26:27] offset:512
	global_store_dwordx2 v245, v[152:153], s[26:27] offset:1024
	global_store_dwordx2 v245, v[154:155], s[26:27] offset:1536
	v_pk_mul_f32 v[164:165], v[164:165], v[242:243] op_sel_hi:[1,0]
	v_pk_mul_f32 v[166:167], v[166:167], v[242:243] op_sel_hi:[1,0]
	v_pk_mul_f32 v[168:169], v[168:169], v[242:243] op_sel_hi:[1,0]
	v_pk_mul_f32 v[170:171], v[170:171], v[242:243] op_sel_hi:[1,0]
	v_pk_mul_f32 v[172:173], v[172:173], v[242:243] op_sel_hi:[1,0]
	v_pk_mul_f32 v[174:175], v[174:175], v[242:243] op_sel_hi:[1,0]
	v_pk_mul_f32 v[176:177], v[176:177], v[242:243] op_sel_hi:[1,0]
	v_pk_mul_f32 v[178:179], v[178:179], v[242:243] op_sel_hi:[1,0]
	v_pk_mul_f32 v[164:165], v[164:165], v[202:203]
	v_pk_mul_f32 v[166:167], v[166:167], v[204:205]
	v_pk_mul_f32 v[168:169], v[168:169], v[206:207]
	v_pk_mul_f32 v[170:171], v[170:171], v[208:209]
	v_pk_mul_f32 v[172:173], v[172:173], v[210:211]
	v_pk_mul_f32 v[174:175], v[174:175], v[212:213]
	v_pk_mul_f32 v[176:177], v[176:177], v[214:215]
	v_pk_mul_f32 v[178:179], v[178:179], v[216:217]
	v_cvt_pk_bf16_f32 v164, v164, v165
	v_cvt_pk_bf16_f32 v165, v166, v167
	v_cvt_pk_bf16_f32 v166, v168, v169
	v_cvt_pk_bf16_f32 v167, v170, v171
	v_cvt_pk_bf16_f32 v168, v172, v173
	v_cvt_pk_bf16_f32 v169, v174, v175
	v_cvt_pk_bf16_f32 v170, v176, v177
	v_cvt_pk_bf16_f32 v171, v178, v179
	s_add_u32 s26, s14, 0x1400000
	s_addc_u32 s27, s15, 0
	global_store_dwordx2 v245, v[164:165], s[26:27] offset:0
	global_store_dwordx2 v245, v[166:167], s[26:27] offset:512
	global_store_dwordx2 v245, v[168:169], s[26:27] offset:1024
	global_store_dwordx2 v245, v[170:171], s[26:27] offset:1536
	s_add_u32 s22, s10, 0x2800000
	s_addc_u32 s23, s11, 0
	s_add_u32 s24, s12, 0x5000000
	s_addc_u32 s25, s13, 0
	global_load_dwordx2 v[100:101], v245, s[22:23] offset:0
	global_load_dwordx2 v[102:103], v245, s[22:23] offset:512
	global_load_dwordx2 v[104:105], v245, s[22:23] offset:1024
	global_load_dwordx2 v[106:107], v245, s[22:23] offset:1536
	global_load_dwordx4 v[108:111], v244, s[24:25] offset:0
	global_load_dwordx4 v[112:115], v244, s[24:25] offset:1024
	global_load_dwordx4 v[116:119], v244, s[24:25] offset:2048
	global_load_dwordx4 v[120:123], v244, s[24:25] offset:3072
	s_add_u32 s22, s10, 0x2c00000
	s_addc_u32 s23, s11, 0
	s_add_u32 s24, s12, 0x5800000
	s_addc_u32 s25, s13, 0
	global_load_dwordx2 v[124:125], v245, s[22:23] offset:0
	global_load_dwordx2 v[126:127], v245, s[22:23] offset:512
	global_load_dwordx2 v[128:129], v245, s[22:23] offset:1024
	global_load_dwordx2 v[130:131], v245, s[22:23] offset:1536
	global_load_dwordx4 v[132:135], v244, s[24:25] offset:0
	global_load_dwordx4 v[136:139], v244, s[24:25] offset:1024
	global_load_dwordx4 v[140:143], v244, s[24:25] offset:2048
	global_load_dwordx4 v[144:147], v244, s[24:25] offset:3072
	s_waitcnt vmcnt(56)
	v_lshlrev_b32_e32 v148, 16, v4
	v_and_b32_e32 v149, 0xffff0000, v4
	v_lshlrev_b32_e32 v150, 16, v5
	v_and_b32_e32 v151, 0xffff0000, v5
	v_lshlrev_b32_e32 v152, 16, v6
	v_and_b32_e32 v153, 0xffff0000, v6
	v_lshlrev_b32_e32 v154, 16, v7
	v_and_b32_e32 v155, 0xffff0000, v7
	v_lshlrev_b32_e32 v156, 16, v8
	v_and_b32_e32 v157, 0xffff0000, v8
	v_lshlrev_b32_e32 v158, 16, v9
	v_and_b32_e32 v159, 0xffff0000, v9
	v_lshlrev_b32_e32 v160, 16, v10
	v_and_b32_e32 v161, 0xffff0000, v10
	v_lshlrev_b32_e32 v162, 16, v11
	v_and_b32_e32 v163, 0xffff0000, v11
	s_waitcnt vmcnt(48)
	v_lshlrev_b32_e32 v164, 16, v28
	v_and_b32_e32 v165, 0xffff0000, v28
	v_lshlrev_b32_e32 v166, 16, v29
	v_and_b32_e32 v167, 0xffff0000, v29
	v_lshlrev_b32_e32 v168, 16, v30
	v_and_b32_e32 v169, 0xffff0000, v30
	v_lshlrev_b32_e32 v170, 16, v31
	v_and_b32_e32 v171, 0xffff0000, v31
	v_lshlrev_b32_e32 v172, 16, v32
	v_and_b32_e32 v173, 0xffff0000, v32
	v_lshlrev_b32_e32 v174, 16, v33
	v_and_b32_e32 v175, 0xffff0000, v33
	v_lshlrev_b32_e32 v176, 16, v34
	v_and_b32_e32 v177, 0xffff0000, v34
	v_lshlrev_b32_e32 v178, 16, v35
	v_and_b32_e32 v179, 0xffff0000, v35
	v_pk_mul_f32 v[236:237], v[148:149], v[148:149]
	v_pk_fma_f32 v[236:237], v[150:151], v[150:151], v[236:237]
	v_pk_fma_f32 v[236:237], v[152:153], v[152:153], v[236:237]
	v_pk_fma_f32 v[236:237], v[154:155], v[154:155], v[236:237]
	v_pk_fma_f32 v[236:237], v[156:157], v[156:157], v[236:237]
	v_pk_fma_f32 v[236:237], v[158:159], v[158:159], v[236:237]
	v_pk_fma_f32 v[236:237], v[160:161], v[160:161], v[236:237]
	v_pk_fma_f32 v[236:237], v[162:163], v[162:163], v[236:237]
	v_pk_mul_f32 v[238:239], v[164:165], v[164:165]
	v_pk_fma_f32 v[238:239], v[166:167], v[166:167], v[238:239]
	v_pk_fma_f32 v[238:239], v[168:169], v[168:169], v[238:239]
	v_pk_fma_f32 v[238:239], v[170:171], v[170:171], v[238:239]
	v_pk_fma_f32 v[238:239], v[172:173], v[172:173], v[238:239]
	v_pk_fma_f32 v[238:239], v[174:175], v[174:175], v[238:239]
	v_pk_fma_f32 v[238:239], v[176:177], v[176:177], v[238:239]
	v_pk_fma_f32 v[238:239], v[178:179], v[178:179], v[238:239]
	v_add_f32_e32 v236, v236, v237
	v_add_f32_e32 v238, v238, v239
	s_nop 1
	v_add_f32_dpp v236, v236, v236 quad_perm:[1,0,3,2] row_mask:0xf bank_mask:0xf
	v_add_f32_dpp v238, v238, v238 quad_perm:[1,0,3,2] row_mask:0xf bank_mask:0xf
	s_nop 1
	v_add_f32_dpp v236, v236, v236 quad_perm:[2,3,0,1] row_mask:0xf bank_mask:0xf
	v_add_f32_dpp v238, v238, v238 quad_perm:[2,3,0,1] row_mask:0xf bank_mask:0xf
	s_nop 1
	v_add_f32_dpp v236, v236, v236 row_half_mirror row_mask:0xf bank_mask:0xf
	v_add_f32_dpp v238, v238, v238 row_half_mirror row_mask:0xf bank_mask:0xf
	s_nop 1
	v_add_f32_dpp v236, v236, v236 row_mirror row_mask:0xf bank_mask:0xf
	v_add_f32_dpp v238, v238, v238 row_mirror row_mask:0xf bank_mask:0xf
	s_nop 1
	v_add_f32_dpp v236, v236, v236 row_bcast:15 row_mask:0xa bank_mask:0xf
	v_add_f32_dpp v238, v238, v238 row_bcast:15 row_mask:0xa bank_mask:0xf
	s_nop 1
	v_add_f32_dpp v236, v236, v236 row_bcast:31 row_mask:0xc bank_mask:0xf
	v_add_f32_dpp v238, v238, v238 row_bcast:31 row_mask:0xc bank_mask:0xf
	s_nop 1
	v_readlane_b32 s2, v236, 63
	v_readlane_b32 s3, v238, 63
	s_nop 1
	v_mov_b32_e32 v240, s2
	v_mov_b32_e32 v242, s3
	v_fmamk_f32 v240, v240, 0x3a800000, v196
	v_fmamk_f32 v242, v242, 0x3a800000, v196
	v_rsq_f32_e32 v240, v240
	v_rsq_f32_e32 v242, v242
	s_nop 0
	v_pk_mul_f32 v[148:149], v[148:149], v[240:241] op_sel_hi:[1,0]
	v_pk_mul_f32 v[150:151], v[150:151], v[240:241] op_sel_hi:[1,0]
	v_pk_mul_f32 v[152:153], v[152:153], v[240:241] op_sel_hi:[1,0]
	v_pk_mul_f32 v[154:155], v[154:155], v[240:241] op_sel_hi:[1,0]
	v_pk_mul_f32 v[156:157], v[156:157], v[240:241] op_sel_hi:[1,0]
	v_pk_mul_f32 v[158:159], v[158:159], v[240:241] op_sel_hi:[1,0]
	v_pk_mul_f32 v[160:161], v[160:161], v[240:241] op_sel_hi:[1,0]
	v_pk_mul_f32 v[162:163], v[162:163], v[240:241] op_sel_hi:[1,0]
	v_pk_fma_f32 v[148:149], v[148:149], v[180:181], v[12:13]
	v_pk_fma_f32 v[150:151], v[150:151], v[182:183], v[14:15]
	v_pk_fma_f32 v[152:153], v[152:153], v[184:185], v[16:17]
	v_pk_fma_f32 v[154:155], v[154:155], v[186:187], v[18:19]
	v_pk_fma_f32 v[156:157], v[156:157], v[188:189], v[20:21]
	v_pk_fma_f32 v[158:159], v[158:159], v[190:191], v[22:23]
	v_pk_fma_f32 v[160:161], v[160:161], v[192:193], v[24:25]
	v_pk_fma_f32 v[162:163], v[162:163], v[194:195], v[26:27]
	v_pk_mul_f32 v[164:165], v[164:165], v[242:243] op_sel_hi:[1,0]
	v_pk_mul_f32 v[166:167], v[166:167], v[242:243] op_sel_hi:[1,0]
	v_pk_mul_f32 v[168:169], v[168:169], v[242:243] op_sel_hi:[1,0]
	v_pk_mul_f32 v[170:171], v[170:171], v[242:243] op_sel_hi:[1,0]
	v_pk_mul_f32 v[172:173], v[172:173], v[242:243] op_sel_hi:[1,0]
	v_pk_mul_f32 v[174:175], v[174:175], v[242:243] op_sel_hi:[1,0]
	v_pk_mul_f32 v[176:177], v[176:177], v[242:243] op_sel_hi:[1,0]
	v_pk_mul_f32 v[178:179], v[178:179], v[242:243] op_sel_hi:[1,0]
	v_pk_fma_f32 v[164:165], v[164:165], v[180:181], v[36:37]
	v_pk_fma_f32 v[166:167], v[166:167], v[182:183], v[38:39]
	v_pk_fma_f32 v[168:169], v[168:169], v[184:185], v[40:41]
	v_pk_fma_f32 v[170:171], v[170:171], v[186:187], v[42:43]
	v_pk_fma_f32 v[172:173], v[172:173], v[188:189], v[44:45]
	v_pk_fma_f32 v[174:175], v[174:175], v[190:191], v[46:47]
	v_pk_fma_f32 v[176:177], v[176:177], v[192:193], v[48:49]
	v_pk_fma_f32 v[178:179], v[178:179], v[194:195], v[50:51]
	v_pk_mul_f32 v[236:237], v[148:149], v[148:149]
	v_pk_fma_f32 v[236:237], v[150:151], v[150:151], v[236:237]
	v_pk_fma_f32 v[236:237], v[152:153], v[152:153], v[236:237]
	v_pk_fma_f32 v[236:237], v[154:155], v[154:155], v[236:237]
	v_pk_fma_f32 v[236:237], v[156:157], v[156:157], v[236:237]
	v_pk_fma_f32 v[236:237], v[158:159], v[158:159], v[236:237]
	v_pk_fma_f32 v[236:237], v[160:161], v[160:161], v[236:237]
	v_pk_fma_f32 v[236:237], v[162:163], v[162:163], v[236:237]
	v_pk_mul_f32 v[238:239], v[164:165], v[164:165]
	v_pk_fma_f32 v[238:239], v[166:167], v[166:167], v[238:239]
	v_pk_fma_f32 v[238:239], v[168:169], v[168:169], v[238:239]
	v_pk_fma_f32 v[238:239], v[170:171], v[170:171], v[238:239]
	v_pk_fma_f32 v[238:239], v[172:173], v[172:173], v[238:239]
	v_pk_fma_f32 v[238:239], v[174:175], v[174:175], v[238:239]
	v_pk_fma_f32 v[238:239], v[176:177], v[176:177], v[238:239]
	v_pk_fma_f32 v[238:239], v[178:179], v[178:179], v[238:239]
	v_add_f32_e32 v236, v236, v237
	v_add_f32_e32 v238, v238, v239
	s_nop 1
	v_add_f32_dpp v236, v236, v236 quad_perm:[1,0,3,2] row_mask:0xf bank_mask:0xf
	v_add_f32_dpp v238, v238, v238 quad_perm:[1,0,3,2] row_mask:0xf bank_mask:0xf
	s_nop 1
	v_add_f32_dpp v236, v236, v236 quad_perm:[2,3,0,1] row_mask:0xf bank_mask:0xf
	v_add_f32_dpp v238, v238, v238 quad_perm:[2,3,0,1] row_mask:0xf bank_mask:0xf
	s_nop 1
	v_add_f32_dpp v236, v236, v236 row_half_mirror row_mask:0xf bank_mask:0xf
	v_add_f32_dpp v238, v238, v238 row_half_mirror row_mask:0xf bank_mask:0xf
	s_nop 1
	v_add_f32_dpp v236, v236, v236 row_mirror row_mask:0xf bank_mask:0xf
	v_add_f32_dpp v238, v238, v238 row_mirror row_mask:0xf bank_mask:0xf
	s_nop 1
	v_add_f32_dpp v236, v236, v236 row_bcast:15 row_mask:0xa bank_mask:0xf
	v_add_f32_dpp v238, v238, v238 row_bcast:15 row_mask:0xa bank_mask:0xf
	s_nop 1
	v_add_f32_dpp v236, v236, v236 row_bcast:31 row_mask:0xc bank_mask:0xf
	v_add_f32_dpp v238, v238, v238 row_bcast:31 row_mask:0xc bank_mask:0xf
	s_nop 1
	v_readlane_b32 s2, v236, 63
	v_readlane_b32 s3, v238, 63
	s_nop 1
	v_mov_b32_e32 v240, s2
	v_mov_b32_e32 v242, s3
	v_fmamk_f32 v240, v240, 0x3a800000, v196
	v_fmamk_f32 v242, v242, 0x3a800000, v196
	v_rsq_f32_e32 v240, v240
	v_rsq_f32_e32 v242, v242
	s_nop 0
	v_pk_mul_f32 v[148:149], v[148:149], v[240:241] op_sel_hi:[1,0]
	v_pk_mul_f32 v[150:151], v[150:151], v[240:241] op_sel_hi:[1,0]
	v_pk_mul_f32 v[152:153], v[152:153], v[240:241] op_sel_hi:[1,0]
	v_pk_mul_f32 v[154:155], v[154:155], v[240:241] op_sel_hi:[1,0]
	v_pk_mul_f32 v[156:157], v[156:157], v[240:241] op_sel_hi:[1,0]
	v_pk_mul_f32 v[158:159], v[158:159], v[240:241] op_sel_hi:[1,0]
	v_pk_mul_f32 v[160:161], v[160:161], v[240:241] op_sel_hi:[1,0]
	v_pk_mul_f32 v[162:163], v[162:163], v[240:241] op_sel_hi:[1,0]
	v_pk_mul_f32 v[148:149], v[148:149], v[202:203]
	v_pk_mul_f32 v[150:151], v[150:151], v[204:205]
	v_pk_mul_f32 v[152:153], v[152:153], v[206:207]
	v_pk_mul_f32 v[154:155], v[154:155], v[208:209]
	v_pk_mul_f32 v[156:157], v[156:157], v[210:211]
	v_pk_mul_f32 v[158:159], v[158:159], v[212:213]
	v_pk_mul_f32 v[160:161], v[160:161], v[214:215]
	v_pk_mul_f32 v[162:163], v[162:163], v[216:217]
	v_cvt_pk_bf16_f32 v148, v148, v149
	v_cvt_pk_bf16_f32 v149, v150, v151
	v_cvt_pk_bf16_f32 v150, v152, v153
	v_cvt_pk_bf16_f32 v151, v154, v155
	v_cvt_pk_bf16_f32 v152, v156, v157
	v_cvt_pk_bf16_f32 v153, v158, v159
	v_cvt_pk_bf16_f32 v154, v160, v161
	v_cvt_pk_bf16_f32 v155, v162, v163
	s_add_u32 s26, s14, 0x1800000
	s_addc_u32 s27, s15, 0
	global_store_dwordx2 v245, v[148:149], s[26:27] offset:0
	global_store_dwordx2 v245, v[150:151], s[26:27] offset:512
	global_store_dwordx2 v245, v[152:153], s[26:27] offset:1024
	global_store_dwordx2 v245, v[154:155], s[26:27] offset:1536
	v_pk_mul_f32 v[164:165], v[164:165], v[242:243] op_sel_hi:[1,0]
	v_pk_mul_f32 v[166:167], v[166:167], v[242:243] op_sel_hi:[1,0]
	v_pk_mul_f32 v[168:169], v[168:169], v[242:243] op_sel_hi:[1,0]
	v_pk_mul_f32 v[170:171], v[170:171], v[242:243] op_sel_hi:[1,0]
	v_pk_mul_f32 v[172:173], v[172:173], v[242:243] op_sel_hi:[1,0]
	v_pk_mul_f32 v[174:175], v[174:175], v[242:243] op_sel_hi:[1,0]
	v_pk_mul_f32 v[176:177], v[176:177], v[242:243] op_sel_hi:[1,0]
	v_pk_mul_f32 v[178:179], v[178:179], v[242:243] op_sel_hi:[1,0]
	v_pk_mul_f32 v[164:165], v[164:165], v[202:203]
	v_pk_mul_f32 v[166:167], v[166:167], v[204:205]
	v_pk_mul_f32 v[168:169], v[168:169], v[206:207]
	v_pk_mul_f32 v[170:171], v[170:171], v[208:209]
	v_pk_mul_f32 v[172:173], v[172:173], v[210:211]
	v_pk_mul_f32 v[174:175], v[174:175], v[212:213]
	v_pk_mul_f32 v[176:177], v[176:177], v[214:215]
	v_pk_mul_f32 v[178:179], v[178:179], v[216:217]
	v_cvt_pk_bf16_f32 v164, v164, v165
	v_cvt_pk_bf16_f32 v165, v166, v167
	v_cvt_pk_bf16_f32 v166, v168, v169
	v_cvt_pk_bf16_f32 v167, v170, v171
	v_cvt_pk_bf16_f32 v168, v172, v173
	v_cvt_pk_bf16_f32 v169, v174, v175
	v_cvt_pk_bf16_f32 v170, v176, v177
	v_cvt_pk_bf16_f32 v171, v178, v179
	s_add_u32 s26, s14, 0x1c00000
	s_addc_u32 s27, s15, 0
	global_store_dwordx2 v245, v[164:165], s[26:27] offset:0
	global_store_dwordx2 v245, v[166:167], s[26:27] offset:512
	global_store_dwordx2 v245, v[168:169], s[26:27] offset:1024
	global_store_dwordx2 v245, v[170:171], s[26:27] offset:1536
	s_add_u32 s22, s10, 0x3000000
	s_addc_u32 s23, s11, 0
	s_add_u32 s24, s12, 0x6000000
	s_addc_u32 s25, s13, 0
	global_load_dwordx2 v[4:5], v245, s[22:23] offset:0
	global_load_dwordx2 v[6:7], v245, s[22:23] offset:512
	global_load_dwordx2 v[8:9], v245, s[22:23] offset:1024
	global_load_dwordx2 v[10:11], v245, s[22:23] offset:1536
	global_load_dwordx4 v[12:15], v244, s[24:25] offset:0
	global_load_dwordx4 v[16:19], v244, s[24:25] offset:1024
	global_load_dwordx4 v[20:23], v244, s[24:25] offset:2048
	global_load_dwordx4 v[24:27], v244, s[24:25] offset:3072
	s_add_u32 s22, s10, 0x3400000
	s_addc_u32 s23, s11, 0
	s_add_u32 s24, s12, 0x6800000
	s_addc_u32 s25, s13, 0
	global_load_dwordx2 v[28:29], v245, s[22:23] offset:0
	global_load_dwordx2 v[30:31], v245, s[22:23] offset:512
	global_load_dwordx2 v[32:33], v245, s[22:23] offset:1024
	global_load_dwordx2 v[34:35], v245, s[22:23] offset:1536
	global_load_dwordx4 v[36:39], v244, s[24:25] offset:0
	global_load_dwordx4 v[40:43], v244, s[24:25] offset:1024
	global_load_dwordx4 v[44:47], v244, s[24:25] offset:2048
	global_load_dwordx4 v[48:51], v244, s[24:25] offset:3072
	s_waitcnt vmcnt(56)
	v_lshlrev_b32_e32 v148, 16, v52
	v_and_b32_e32 v149, 0xffff0000, v52
	v_lshlrev_b32_e32 v150, 16, v53
	v_and_b32_e32 v151, 0xffff0000, v53
	v_lshlrev_b32_e32 v152, 16, v54
	v_and_b32_e32 v153, 0xffff0000, v54
	v_lshlrev_b32_e32 v154, 16, v55
	v_and_b32_e32 v155, 0xffff0000, v55
	v_lshlrev_b32_e32 v156, 16, v56
	v_and_b32_e32 v157, 0xffff0000, v56
	v_lshlrev_b32_e32 v158, 16, v57
	v_and_b32_e32 v159, 0xffff0000, v57
	v_lshlrev_b32_e32 v160, 16, v58
	v_and_b32_e32 v161, 0xffff0000, v58
	v_lshlrev_b32_e32 v162, 16, v59
	v_and_b32_e32 v163, 0xffff0000, v59
	s_waitcnt vmcnt(48)
	v_lshlrev_b32_e32 v164, 16, v76
	v_and_b32_e32 v165, 0xffff0000, v76
	v_lshlrev_b32_e32 v166, 16, v77
	v_and_b32_e32 v167, 0xffff0000, v77
	v_lshlrev_b32_e32 v168, 16, v78
	v_and_b32_e32 v169, 0xffff0000, v78
	v_lshlrev_b32_e32 v170, 16, v79
	v_and_b32_e32 v171, 0xffff0000, v79
	v_lshlrev_b32_e32 v172, 16, v80
	v_and_b32_e32 v173, 0xffff0000, v80
	v_lshlrev_b32_e32 v174, 16, v81
	v_and_b32_e32 v175, 0xffff0000, v81
	v_lshlrev_b32_e32 v176, 16, v82
	v_and_b32_e32 v177, 0xffff0000, v82
	v_lshlrev_b32_e32 v178, 16, v83
	v_and_b32_e32 v179, 0xffff0000, v83
	v_pk_mul_f32 v[236:237], v[148:149], v[148:149]
	v_pk_fma_f32 v[236:237], v[150:151], v[150:151], v[236:237]
	v_pk_fma_f32 v[236:237], v[152:153], v[152:153], v[236:237]
	v_pk_fma_f32 v[236:237], v[154:155], v[154:155], v[236:237]
	v_pk_fma_f32 v[236:237], v[156:157], v[156:157], v[236:237]
	v_pk_fma_f32 v[236:237], v[158:159], v[158:159], v[236:237]
	v_pk_fma_f32 v[236:237], v[160:161], v[160:161], v[236:237]
	v_pk_fma_f32 v[236:237], v[162:163], v[162:163], v[236:237]
	v_pk_mul_f32 v[238:239], v[164:165], v[164:165]
	v_pk_fma_f32 v[238:239], v[166:167], v[166:167], v[238:239]
	v_pk_fma_f32 v[238:239], v[168:169], v[168:169], v[238:239]
	v_pk_fma_f32 v[238:239], v[170:171], v[170:171], v[238:239]
	v_pk_fma_f32 v[238:239], v[172:173], v[172:173], v[238:239]
	v_pk_fma_f32 v[238:239], v[174:175], v[174:175], v[238:239]
	v_pk_fma_f32 v[238:239], v[176:177], v[176:177], v[238:239]
	v_pk_fma_f32 v[238:239], v[178:179], v[178:179], v[238:239]
	v_add_f32_e32 v236, v236, v237
	v_add_f32_e32 v238, v238, v239
	s_nop 1
	v_add_f32_dpp v236, v236, v236 quad_perm:[1,0,3,2] row_mask:0xf bank_mask:0xf
	v_add_f32_dpp v238, v238, v238 quad_perm:[1,0,3,2] row_mask:0xf bank_mask:0xf
	s_nop 1
	v_add_f32_dpp v236, v236, v236 quad_perm:[2,3,0,1] row_mask:0xf bank_mask:0xf
	v_add_f32_dpp v238, v238, v238 quad_perm:[2,3,0,1] row_mask:0xf bank_mask:0xf
	s_nop 1
	v_add_f32_dpp v236, v236, v236 row_half_mirror row_mask:0xf bank_mask:0xf
	v_add_f32_dpp v238, v238, v238 row_half_mirror row_mask:0xf bank_mask:0xf
	s_nop 1
	v_add_f32_dpp v236, v236, v236 row_mirror row_mask:0xf bank_mask:0xf
	v_add_f32_dpp v238, v238, v238 row_mirror row_mask:0xf bank_mask:0xf
	s_nop 1
	v_add_f32_dpp v236, v236, v236 row_bcast:15 row_mask:0xa bank_mask:0xf
	v_add_f32_dpp v238, v238, v238 row_bcast:15 row_mask:0xa bank_mask:0xf
	s_nop 1
	v_add_f32_dpp v236, v236, v236 row_bcast:31 row_mask:0xc bank_mask:0xf
	v_add_f32_dpp v238, v238, v238 row_bcast:31 row_mask:0xc bank_mask:0xf
	s_nop 1
	v_readlane_b32 s2, v236, 63
	v_readlane_b32 s3, v238, 63
	s_nop 1
	v_mov_b32_e32 v240, s2
	v_mov_b32_e32 v242, s3
	v_fmamk_f32 v240, v240, 0x3a800000, v196
	v_fmamk_f32 v242, v242, 0x3a800000, v196
	v_rsq_f32_e32 v240, v240
	v_rsq_f32_e32 v242, v242
	s_nop 0
	v_pk_mul_f32 v[148:149], v[148:149], v[240:241] op_sel_hi:[1,0]
	v_pk_mul_f32 v[150:151], v[150:151], v[240:241] op_sel_hi:[1,0]
	v_pk_mul_f32 v[152:153], v[152:153], v[240:241] op_sel_hi:[1,0]
	v_pk_mul_f32 v[154:155], v[154:155], v[240:241] op_sel_hi:[1,0]
	v_pk_mul_f32 v[156:157], v[156:157], v[240:241] op_sel_hi:[1,0]
	v_pk_mul_f32 v[158:159], v[158:159], v[240:241] op_sel_hi:[1,0]
	v_pk_mul_f32 v[160:161], v[160:161], v[240:241] op_sel_hi:[1,0]
	v_pk_mul_f32 v[162:163], v[162:163], v[240:241] op_sel_hi:[1,0]
	v_pk_fma_f32 v[148:149], v[148:149], v[180:181], v[60:61]
	v_pk_fma_f32 v[150:151], v[150:151], v[182:183], v[62:63]
	v_pk_fma_f32 v[152:153], v[152:153], v[184:185], v[64:65]
	v_pk_fma_f32 v[154:155], v[154:155], v[186:187], v[66:67]
	v_pk_fma_f32 v[156:157], v[156:157], v[188:189], v[68:69]
	v_pk_fma_f32 v[158:159], v[158:159], v[190:191], v[70:71]
	v_pk_fma_f32 v[160:161], v[160:161], v[192:193], v[72:73]
	v_pk_fma_f32 v[162:163], v[162:163], v[194:195], v[74:75]
	v_pk_mul_f32 v[164:165], v[164:165], v[242:243] op_sel_hi:[1,0]
	v_pk_mul_f32 v[166:167], v[166:167], v[242:243] op_sel_hi:[1,0]
	v_pk_mul_f32 v[168:169], v[168:169], v[242:243] op_sel_hi:[1,0]
	v_pk_mul_f32 v[170:171], v[170:171], v[242:243] op_sel_hi:[1,0]
	v_pk_mul_f32 v[172:173], v[172:173], v[242:243] op_sel_hi:[1,0]
	v_pk_mul_f32 v[174:175], v[174:175], v[242:243] op_sel_hi:[1,0]
	v_pk_mul_f32 v[176:177], v[176:177], v[242:243] op_sel_hi:[1,0]
	v_pk_mul_f32 v[178:179], v[178:179], v[242:243] op_sel_hi:[1,0]
	v_pk_fma_f32 v[164:165], v[164:165], v[180:181], v[84:85]
	v_pk_fma_f32 v[166:167], v[166:167], v[182:183], v[86:87]
	v_pk_fma_f32 v[168:169], v[168:169], v[184:185], v[88:89]
	v_pk_fma_f32 v[170:171], v[170:171], v[186:187], v[90:91]
	v_pk_fma_f32 v[172:173], v[172:173], v[188:189], v[92:93]
	v_pk_fma_f32 v[174:175], v[174:175], v[190:191], v[94:95]
	v_pk_fma_f32 v[176:177], v[176:177], v[192:193], v[96:97]
	v_pk_fma_f32 v[178:179], v[178:179], v[194:195], v[98:99]
	v_pk_mul_f32 v[236:237], v[148:149], v[148:149]
	v_pk_fma_f32 v[236:237], v[150:151], v[150:151], v[236:237]
	v_pk_fma_f32 v[236:237], v[152:153], v[152:153], v[236:237]
	v_pk_fma_f32 v[236:237], v[154:155], v[154:155], v[236:237]
	v_pk_fma_f32 v[236:237], v[156:157], v[156:157], v[236:237]
	v_pk_fma_f32 v[236:237], v[158:159], v[158:159], v[236:237]
	v_pk_fma_f32 v[236:237], v[160:161], v[160:161], v[236:237]
	v_pk_fma_f32 v[236:237], v[162:163], v[162:163], v[236:237]
	v_pk_mul_f32 v[238:239], v[164:165], v[164:165]
	v_pk_fma_f32 v[238:239], v[166:167], v[166:167], v[238:239]
	v_pk_fma_f32 v[238:239], v[168:169], v[168:169], v[238:239]
	v_pk_fma_f32 v[238:239], v[170:171], v[170:171], v[238:239]
	v_pk_fma_f32 v[238:239], v[172:173], v[172:173], v[238:239]
	v_pk_fma_f32 v[238:239], v[174:175], v[174:175], v[238:239]
	v_pk_fma_f32 v[238:239], v[176:177], v[176:177], v[238:239]
	v_pk_fma_f32 v[238:239], v[178:179], v[178:179], v[238:239]
	v_add_f32_e32 v236, v236, v237
	v_add_f32_e32 v238, v238, v239
	s_nop 1
	v_add_f32_dpp v236, v236, v236 quad_perm:[1,0,3,2] row_mask:0xf bank_mask:0xf
	v_add_f32_dpp v238, v238, v238 quad_perm:[1,0,3,2] row_mask:0xf bank_mask:0xf
	s_nop 1
	v_add_f32_dpp v236, v236, v236 quad_perm:[2,3,0,1] row_mask:0xf bank_mask:0xf
	v_add_f32_dpp v238, v238, v238 quad_perm:[2,3,0,1] row_mask:0xf bank_mask:0xf
	s_nop 1
	v_add_f32_dpp v236, v236, v236 row_half_mirror row_mask:0xf bank_mask:0xf
	v_add_f32_dpp v238, v238, v238 row_half_mirror row_mask:0xf bank_mask:0xf
	s_nop 1
	v_add_f32_dpp v236, v236, v236 row_mirror row_mask:0xf bank_mask:0xf
	v_add_f32_dpp v238, v238, v238 row_mirror row_mask:0xf bank_mask:0xf
	s_nop 1
	v_add_f32_dpp v236, v236, v236 row_bcast:15 row_mask:0xa bank_mask:0xf
	v_add_f32_dpp v238, v238, v238 row_bcast:15 row_mask:0xa bank_mask:0xf
	s_nop 1
	v_add_f32_dpp v236, v236, v236 row_bcast:31 row_mask:0xc bank_mask:0xf
	v_add_f32_dpp v238, v238, v238 row_bcast:31 row_mask:0xc bank_mask:0xf
	s_nop 1
	v_readlane_b32 s2, v236, 63
	v_readlane_b32 s3, v238, 63
	s_nop 1
	v_mov_b32_e32 v240, s2
	v_mov_b32_e32 v242, s3
	v_fmamk_f32 v240, v240, 0x3a800000, v196
	v_fmamk_f32 v242, v242, 0x3a800000, v196
	v_rsq_f32_e32 v240, v240
	v_rsq_f32_e32 v242, v242
	s_nop 0
	v_pk_mul_f32 v[148:149], v[148:149], v[240:241] op_sel_hi:[1,0]
	v_pk_mul_f32 v[150:151], v[150:151], v[240:241] op_sel_hi:[1,0]
	v_pk_mul_f32 v[152:153], v[152:153], v[240:241] op_sel_hi:[1,0]
	v_pk_mul_f32 v[154:155], v[154:155], v[240:241] op_sel_hi:[1,0]
	v_pk_mul_f32 v[156:157], v[156:157], v[240:241] op_sel_hi:[1,0]
	v_pk_mul_f32 v[158:159], v[158:159], v[240:241] op_sel_hi:[1,0]
	v_pk_mul_f32 v[160:161], v[160:161], v[240:241] op_sel_hi:[1,0]
	v_pk_mul_f32 v[162:163], v[162:163], v[240:241] op_sel_hi:[1,0]
	v_pk_mul_f32 v[148:149], v[148:149], v[202:203]
	v_pk_mul_f32 v[150:151], v[150:151], v[204:205]
	v_pk_mul_f32 v[152:153], v[152:153], v[206:207]
	v_pk_mul_f32 v[154:155], v[154:155], v[208:209]
	v_pk_mul_f32 v[156:157], v[156:157], v[210:211]
	v_pk_mul_f32 v[158:159], v[158:159], v[212:213]
	v_pk_mul_f32 v[160:161], v[160:161], v[214:215]
	v_pk_mul_f32 v[162:163], v[162:163], v[216:217]
	v_cvt_pk_bf16_f32 v148, v148, v149
	v_cvt_pk_bf16_f32 v149, v150, v151
	v_cvt_pk_bf16_f32 v150, v152, v153
	v_cvt_pk_bf16_f32 v151, v154, v155
	v_cvt_pk_bf16_f32 v152, v156, v157
	v_cvt_pk_bf16_f32 v153, v158, v159
	v_cvt_pk_bf16_f32 v154, v160, v161
	v_cvt_pk_bf16_f32 v155, v162, v163
	s_add_u32 s26, s14, 0x2000000
	s_addc_u32 s27, s15, 0
	global_store_dwordx2 v245, v[148:149], s[26:27] offset:0
	global_store_dwordx2 v245, v[150:151], s[26:27] offset:512
	global_store_dwordx2 v245, v[152:153], s[26:27] offset:1024
	global_store_dwordx2 v245, v[154:155], s[26:27] offset:1536
	v_pk_mul_f32 v[164:165], v[164:165], v[242:243] op_sel_hi:[1,0]
	v_pk_mul_f32 v[166:167], v[166:167], v[242:243] op_sel_hi:[1,0]
	v_pk_mul_f32 v[168:169], v[168:169], v[242:243] op_sel_hi:[1,0]
	v_pk_mul_f32 v[170:171], v[170:171], v[242:243] op_sel_hi:[1,0]
	v_pk_mul_f32 v[172:173], v[172:173], v[242:243] op_sel_hi:[1,0]
	v_pk_mul_f32 v[174:175], v[174:175], v[242:243] op_sel_hi:[1,0]
	v_pk_mul_f32 v[176:177], v[176:177], v[242:243] op_sel_hi:[1,0]
	v_pk_mul_f32 v[178:179], v[178:179], v[242:243] op_sel_hi:[1,0]
	v_pk_mul_f32 v[164:165], v[164:165], v[202:203]
	v_pk_mul_f32 v[166:167], v[166:167], v[204:205]
	v_pk_mul_f32 v[168:169], v[168:169], v[206:207]
	v_pk_mul_f32 v[170:171], v[170:171], v[208:209]
	v_pk_mul_f32 v[172:173], v[172:173], v[210:211]
	v_pk_mul_f32 v[174:175], v[174:175], v[212:213]
	v_pk_mul_f32 v[176:177], v[176:177], v[214:215]
	v_pk_mul_f32 v[178:179], v[178:179], v[216:217]
	v_cvt_pk_bf16_f32 v164, v164, v165
	v_cvt_pk_bf16_f32 v165, v166, v167
	v_cvt_pk_bf16_f32 v166, v168, v169
	v_cvt_pk_bf16_f32 v167, v170, v171
	v_cvt_pk_bf16_f32 v168, v172, v173
	v_cvt_pk_bf16_f32 v169, v174, v175
	v_cvt_pk_bf16_f32 v170, v176, v177
	v_cvt_pk_bf16_f32 v171, v178, v179
	s_add_u32 s26, s14, 0x2400000
	s_addc_u32 s27, s15, 0
	global_store_dwordx2 v245, v[164:165], s[26:27] offset:0
	global_store_dwordx2 v245, v[166:167], s[26:27] offset:512
	global_store_dwordx2 v245, v[168:169], s[26:27] offset:1024
	global_store_dwordx2 v245, v[170:171], s[26:27] offset:1536
	s_add_u32 s22, s10, 0x3800000
	s_addc_u32 s23, s11, 0
	s_add_u32 s24, s12, 0x7000000
	s_addc_u32 s25, s13, 0
	global_load_dwordx2 v[52:53], v245, s[22:23] offset:0
	global_load_dwordx2 v[54:55], v245, s[22:23] offset:512
	global_load_dwordx2 v[56:57], v245, s[22:23] offset:1024
	global_load_dwordx2 v[58:59], v245, s[22:23] offset:1536
	global_load_dwordx4 v[60:63], v244, s[24:25] offset:0
	global_load_dwordx4 v[64:67], v244, s[24:25] offset:1024
	global_load_dwordx4 v[68:71], v244, s[24:25] offset:2048
	global_load_dwordx4 v[72:75], v244, s[24:25] offset:3072
	s_add_u32 s22, s10, 0x3c00000
	s_addc_u32 s23, s11, 0
	s_add_u32 s24, s12, 0x7800000
	s_addc_u32 s25, s13, 0
	global_load_dwordx2 v[76:77], v245, s[22:23] offset:0
	global_load_dwordx2 v[78:79], v245, s[22:23] offset:512
	global_load_dwordx2 v[80:81], v245, s[22:23] offset:1024
	global_load_dwordx2 v[82:83], v245, s[22:23] offset:1536
	global_load_dwordx4 v[84:87], v244, s[24:25] offset:0
	global_load_dwordx4 v[88:91], v244, s[24:25] offset:1024
	global_load_dwordx4 v[92:95], v244, s[24:25] offset:2048
	global_load_dwordx4 v[96:99], v244, s[24:25] offset:3072
	s_waitcnt vmcnt(56)
	v_lshlrev_b32_e32 v148, 16, v100
	v_and_b32_e32 v149, 0xffff0000, v100
	v_lshlrev_b32_e32 v150, 16, v101
	v_and_b32_e32 v151, 0xffff0000, v101
	v_lshlrev_b32_e32 v152, 16, v102
	v_and_b32_e32 v153, 0xffff0000, v102
	v_lshlrev_b32_e32 v154, 16, v103
	v_and_b32_e32 v155, 0xffff0000, v103
	v_lshlrev_b32_e32 v156, 16, v104
	v_and_b32_e32 v157, 0xffff0000, v104
	v_lshlrev_b32_e32 v158, 16, v105
	v_and_b32_e32 v159, 0xffff0000, v105
	v_lshlrev_b32_e32 v160, 16, v106
	v_and_b32_e32 v161, 0xffff0000, v106
	v_lshlrev_b32_e32 v162, 16, v107
	v_and_b32_e32 v163, 0xffff0000, v107
	s_waitcnt vmcnt(48)
	v_lshlrev_b32_e32 v164, 16, v124
	v_and_b32_e32 v165, 0xffff0000, v124
	v_lshlrev_b32_e32 v166, 16, v125
	v_and_b32_e32 v167, 0xffff0000, v125
	v_lshlrev_b32_e32 v168, 16, v126
	v_and_b32_e32 v169, 0xffff0000, v126
	v_lshlrev_b32_e32 v170, 16, v127
	v_and_b32_e32 v171, 0xffff0000, v127
	v_lshlrev_b32_e32 v172, 16, v128
	v_and_b32_e32 v173, 0xffff0000, v128
	v_lshlrev_b32_e32 v174, 16, v129
	v_and_b32_e32 v175, 0xffff0000, v129
	v_lshlrev_b32_e32 v176, 16, v130
	v_and_b32_e32 v177, 0xffff0000, v130
	v_lshlrev_b32_e32 v178, 16, v131
	v_and_b32_e32 v179, 0xffff0000, v131
	v_pk_mul_f32 v[236:237], v[148:149], v[148:149]
	v_pk_fma_f32 v[236:237], v[150:151], v[150:151], v[236:237]
	v_pk_fma_f32 v[236:237], v[152:153], v[152:153], v[236:237]
	v_pk_fma_f32 v[236:237], v[154:155], v[154:155], v[236:237]
	v_pk_fma_f32 v[236:237], v[156:157], v[156:157], v[236:237]
	v_pk_fma_f32 v[236:237], v[158:159], v[158:159], v[236:237]
	v_pk_fma_f32 v[236:237], v[160:161], v[160:161], v[236:237]
	v_pk_fma_f32 v[236:237], v[162:163], v[162:163], v[236:237]
	v_pk_mul_f32 v[238:239], v[164:165], v[164:165]
	v_pk_fma_f32 v[238:239], v[166:167], v[166:167], v[238:239]
	v_pk_fma_f32 v[238:239], v[168:169], v[168:169], v[238:239]
	v_pk_fma_f32 v[238:239], v[170:171], v[170:171], v[238:239]
	v_pk_fma_f32 v[238:239], v[172:173], v[172:173], v[238:239]
	v_pk_fma_f32 v[238:239], v[174:175], v[174:175], v[238:239]
	v_pk_fma_f32 v[238:239], v[176:177], v[176:177], v[238:239]
	v_pk_fma_f32 v[238:239], v[178:179], v[178:179], v[238:239]
	v_add_f32_e32 v236, v236, v237
	v_add_f32_e32 v238, v238, v239
	s_nop 1
	v_add_f32_dpp v236, v236, v236 quad_perm:[1,0,3,2] row_mask:0xf bank_mask:0xf
	v_add_f32_dpp v238, v238, v238 quad_perm:[1,0,3,2] row_mask:0xf bank_mask:0xf
	s_nop 1
	v_add_f32_dpp v236, v236, v236 quad_perm:[2,3,0,1] row_mask:0xf bank_mask:0xf
	v_add_f32_dpp v238, v238, v238 quad_perm:[2,3,0,1] row_mask:0xf bank_mask:0xf
	s_nop 1
	v_add_f32_dpp v236, v236, v236 row_half_mirror row_mask:0xf bank_mask:0xf
	v_add_f32_dpp v238, v238, v238 row_half_mirror row_mask:0xf bank_mask:0xf
	s_nop 1
	v_add_f32_dpp v236, v236, v236 row_mirror row_mask:0xf bank_mask:0xf
	v_add_f32_dpp v238, v238, v238 row_mirror row_mask:0xf bank_mask:0xf
	s_nop 1
	v_add_f32_dpp v236, v236, v236 row_bcast:15 row_mask:0xa bank_mask:0xf
	v_add_f32_dpp v238, v238, v238 row_bcast:15 row_mask:0xa bank_mask:0xf
	s_nop 1
	v_add_f32_dpp v236, v236, v236 row_bcast:31 row_mask:0xc bank_mask:0xf
	v_add_f32_dpp v238, v238, v238 row_bcast:31 row_mask:0xc bank_mask:0xf
	s_nop 1
	v_readlane_b32 s2, v236, 63
	v_readlane_b32 s3, v238, 63
	s_nop 1
	v_mov_b32_e32 v240, s2
	v_mov_b32_e32 v242, s3
	v_fmamk_f32 v240, v240, 0x3a800000, v196
	v_fmamk_f32 v242, v242, 0x3a800000, v196
	v_rsq_f32_e32 v240, v240
	v_rsq_f32_e32 v242, v242
	s_nop 0
	v_pk_mul_f32 v[148:149], v[148:149], v[240:241] op_sel_hi:[1,0]
	v_pk_mul_f32 v[150:151], v[150:151], v[240:241] op_sel_hi:[1,0]
	v_pk_mul_f32 v[152:153], v[152:153], v[240:241] op_sel_hi:[1,0]
	v_pk_mul_f32 v[154:155], v[154:155], v[240:241] op_sel_hi:[1,0]
	v_pk_mul_f32 v[156:157], v[156:157], v[240:241] op_sel_hi:[1,0]
	v_pk_mul_f32 v[158:159], v[158:159], v[240:241] op_sel_hi:[1,0]
	v_pk_mul_f32 v[160:161], v[160:161], v[240:241] op_sel_hi:[1,0]
	v_pk_mul_f32 v[162:163], v[162:163], v[240:241] op_sel_hi:[1,0]
	v_pk_fma_f32 v[148:149], v[148:149], v[180:181], v[108:109]
	v_pk_fma_f32 v[150:151], v[150:151], v[182:183], v[110:111]
	v_pk_fma_f32 v[152:153], v[152:153], v[184:185], v[112:113]
	v_pk_fma_f32 v[154:155], v[154:155], v[186:187], v[114:115]
	v_pk_fma_f32 v[156:157], v[156:157], v[188:189], v[116:117]
	v_pk_fma_f32 v[158:159], v[158:159], v[190:191], v[118:119]
	v_pk_fma_f32 v[160:161], v[160:161], v[192:193], v[120:121]
	v_pk_fma_f32 v[162:163], v[162:163], v[194:195], v[122:123]
	v_pk_mul_f32 v[164:165], v[164:165], v[242:243] op_sel_hi:[1,0]
	v_pk_mul_f32 v[166:167], v[166:167], v[242:243] op_sel_hi:[1,0]
	v_pk_mul_f32 v[168:169], v[168:169], v[242:243] op_sel_hi:[1,0]
	v_pk_mul_f32 v[170:171], v[170:171], v[242:243] op_sel_hi:[1,0]
	v_pk_mul_f32 v[172:173], v[172:173], v[242:243] op_sel_hi:[1,0]
	v_pk_mul_f32 v[174:175], v[174:175], v[242:243] op_sel_hi:[1,0]
	v_pk_mul_f32 v[176:177], v[176:177], v[242:243] op_sel_hi:[1,0]
	v_pk_mul_f32 v[178:179], v[178:179], v[242:243] op_sel_hi:[1,0]
	v_pk_fma_f32 v[164:165], v[164:165], v[180:181], v[132:133]
	v_pk_fma_f32 v[166:167], v[166:167], v[182:183], v[134:135]
	v_pk_fma_f32 v[168:169], v[168:169], v[184:185], v[136:137]
	v_pk_fma_f32 v[170:171], v[170:171], v[186:187], v[138:139]
	v_pk_fma_f32 v[172:173], v[172:173], v[188:189], v[140:141]
	v_pk_fma_f32 v[174:175], v[174:175], v[190:191], v[142:143]
	v_pk_fma_f32 v[176:177], v[176:177], v[192:193], v[144:145]
	v_pk_fma_f32 v[178:179], v[178:179], v[194:195], v[146:147]
	v_pk_mul_f32 v[236:237], v[148:149], v[148:149]
	v_pk_fma_f32 v[236:237], v[150:151], v[150:151], v[236:237]
	v_pk_fma_f32 v[236:237], v[152:153], v[152:153], v[236:237]
	v_pk_fma_f32 v[236:237], v[154:155], v[154:155], v[236:237]
	v_pk_fma_f32 v[236:237], v[156:157], v[156:157], v[236:237]
	v_pk_fma_f32 v[236:237], v[158:159], v[158:159], v[236:237]
	v_pk_fma_f32 v[236:237], v[160:161], v[160:161], v[236:237]
	v_pk_fma_f32 v[236:237], v[162:163], v[162:163], v[236:237]
	v_pk_mul_f32 v[238:239], v[164:165], v[164:165]
	v_pk_fma_f32 v[238:239], v[166:167], v[166:167], v[238:239]
	v_pk_fma_f32 v[238:239], v[168:169], v[168:169], v[238:239]
	v_pk_fma_f32 v[238:239], v[170:171], v[170:171], v[238:239]
	v_pk_fma_f32 v[238:239], v[172:173], v[172:173], v[238:239]
	v_pk_fma_f32 v[238:239], v[174:175], v[174:175], v[238:239]
	v_pk_fma_f32 v[238:239], v[176:177], v[176:177], v[238:239]
	v_pk_fma_f32 v[238:239], v[178:179], v[178:179], v[238:239]
	v_add_f32_e32 v236, v236, v237
	v_add_f32_e32 v238, v238, v239
	s_nop 1
	v_add_f32_dpp v236, v236, v236 quad_perm:[1,0,3,2] row_mask:0xf bank_mask:0xf
	v_add_f32_dpp v238, v238, v238 quad_perm:[1,0,3,2] row_mask:0xf bank_mask:0xf
	s_nop 1
	v_add_f32_dpp v236, v236, v236 quad_perm:[2,3,0,1] row_mask:0xf bank_mask:0xf
	v_add_f32_dpp v238, v238, v238 quad_perm:[2,3,0,1] row_mask:0xf bank_mask:0xf
	s_nop 1
	v_add_f32_dpp v236, v236, v236 row_half_mirror row_mask:0xf bank_mask:0xf
	v_add_f32_dpp v238, v238, v238 row_half_mirror row_mask:0xf bank_mask:0xf
	s_nop 1
	v_add_f32_dpp v236, v236, v236 row_mirror row_mask:0xf bank_mask:0xf
	v_add_f32_dpp v238, v238, v238 row_mirror row_mask:0xf bank_mask:0xf
	s_nop 1
	v_add_f32_dpp v236, v236, v236 row_bcast:15 row_mask:0xa bank_mask:0xf
	v_add_f32_dpp v238, v238, v238 row_bcast:15 row_mask:0xa bank_mask:0xf
	s_nop 1
	v_add_f32_dpp v236, v236, v236 row_bcast:31 row_mask:0xc bank_mask:0xf
	v_add_f32_dpp v238, v238, v238 row_bcast:31 row_mask:0xc bank_mask:0xf
	s_nop 1
	v_readlane_b32 s2, v236, 63
	v_readlane_b32 s3, v238, 63
	s_nop 1
	v_mov_b32_e32 v240, s2
	v_mov_b32_e32 v242, s3
	v_fmamk_f32 v240, v240, 0x3a800000, v196
	v_fmamk_f32 v242, v242, 0x3a800000, v196
	v_rsq_f32_e32 v240, v240
	v_rsq_f32_e32 v242, v242
	s_nop 0
	v_pk_mul_f32 v[148:149], v[148:149], v[240:241] op_sel_hi:[1,0]
	v_pk_mul_f32 v[150:151], v[150:151], v[240:241] op_sel_hi:[1,0]
	v_pk_mul_f32 v[152:153], v[152:153], v[240:241] op_sel_hi:[1,0]
	v_pk_mul_f32 v[154:155], v[154:155], v[240:241] op_sel_hi:[1,0]
	v_pk_mul_f32 v[156:157], v[156:157], v[240:241] op_sel_hi:[1,0]
	v_pk_mul_f32 v[158:159], v[158:159], v[240:241] op_sel_hi:[1,0]
	v_pk_mul_f32 v[160:161], v[160:161], v[240:241] op_sel_hi:[1,0]
	v_pk_mul_f32 v[162:163], v[162:163], v[240:241] op_sel_hi:[1,0]
	v_pk_mul_f32 v[148:149], v[148:149], v[202:203]
	v_pk_mul_f32 v[150:151], v[150:151], v[204:205]
	v_pk_mul_f32 v[152:153], v[152:153], v[206:207]
	v_pk_mul_f32 v[154:155], v[154:155], v[208:209]
	v_pk_mul_f32 v[156:157], v[156:157], v[210:211]
	v_pk_mul_f32 v[158:159], v[158:159], v[212:213]
	v_pk_mul_f32 v[160:161], v[160:161], v[214:215]
	v_pk_mul_f32 v[162:163], v[162:163], v[216:217]
	v_cvt_pk_bf16_f32 v148, v148, v149
	v_cvt_pk_bf16_f32 v149, v150, v151
	v_cvt_pk_bf16_f32 v150, v152, v153
	v_cvt_pk_bf16_f32 v151, v154, v155
	v_cvt_pk_bf16_f32 v152, v156, v157
	v_cvt_pk_bf16_f32 v153, v158, v159
	v_cvt_pk_bf16_f32 v154, v160, v161
	v_cvt_pk_bf16_f32 v155, v162, v163
	s_add_u32 s26, s14, 0x2800000
	s_addc_u32 s27, s15, 0
	global_store_dwordx2 v245, v[148:149], s[26:27] offset:0
	global_store_dwordx2 v245, v[150:151], s[26:27] offset:512
	global_store_dwordx2 v245, v[152:153], s[26:27] offset:1024
	global_store_dwordx2 v245, v[154:155], s[26:27] offset:1536
	v_pk_mul_f32 v[164:165], v[164:165], v[242:243] op_sel_hi:[1,0]
	v_pk_mul_f32 v[166:167], v[166:167], v[242:243] op_sel_hi:[1,0]
	v_pk_mul_f32 v[168:169], v[168:169], v[242:243] op_sel_hi:[1,0]
	v_pk_mul_f32 v[170:171], v[170:171], v[242:243] op_sel_hi:[1,0]
	v_pk_mul_f32 v[172:173], v[172:173], v[242:243] op_sel_hi:[1,0]
	v_pk_mul_f32 v[174:175], v[174:175], v[242:243] op_sel_hi:[1,0]
	v_pk_mul_f32 v[176:177], v[176:177], v[242:243] op_sel_hi:[1,0]
	v_pk_mul_f32 v[178:179], v[178:179], v[242:243] op_sel_hi:[1,0]
	v_pk_mul_f32 v[164:165], v[164:165], v[202:203]
	v_pk_mul_f32 v[166:167], v[166:167], v[204:205]
	v_pk_mul_f32 v[168:169], v[168:169], v[206:207]
	v_pk_mul_f32 v[170:171], v[170:171], v[208:209]
	v_pk_mul_f32 v[172:173], v[172:173], v[210:211]
	v_pk_mul_f32 v[174:175], v[174:175], v[212:213]
	v_pk_mul_f32 v[176:177], v[176:177], v[214:215]
	v_pk_mul_f32 v[178:179], v[178:179], v[216:217]
	v_cvt_pk_bf16_f32 v164, v164, v165
	v_cvt_pk_bf16_f32 v165, v166, v167
	v_cvt_pk_bf16_f32 v166, v168, v169
	v_cvt_pk_bf16_f32 v167, v170, v171
	v_cvt_pk_bf16_f32 v168, v172, v173
	v_cvt_pk_bf16_f32 v169, v174, v175
	v_cvt_pk_bf16_f32 v170, v176, v177
	v_cvt_pk_bf16_f32 v171, v178, v179
	s_add_u32 s26, s14, 0x2c00000
	s_addc_u32 s27, s15, 0
	global_store_dwordx2 v245, v[164:165], s[26:27] offset:0
	global_store_dwordx2 v245, v[166:167], s[26:27] offset:512
	global_store_dwordx2 v245, v[168:169], s[26:27] offset:1024
	global_store_dwordx2 v245, v[170:171], s[26:27] offset:1536
	s_waitcnt vmcnt(40)
	v_lshlrev_b32_e32 v148, 16, v4
	v_and_b32_e32 v149, 0xffff0000, v4
	v_lshlrev_b32_e32 v150, 16, v5
	v_and_b32_e32 v151, 0xffff0000, v5
	v_lshlrev_b32_e32 v152, 16, v6
	v_and_b32_e32 v153, 0xffff0000, v6
	v_lshlrev_b32_e32 v154, 16, v7
	v_and_b32_e32 v155, 0xffff0000, v7
	v_lshlrev_b32_e32 v156, 16, v8
	v_and_b32_e32 v157, 0xffff0000, v8
	v_lshlrev_b32_e32 v158, 16, v9
	v_and_b32_e32 v159, 0xffff0000, v9
	v_lshlrev_b32_e32 v160, 16, v10
	v_and_b32_e32 v161, 0xffff0000, v10
	v_lshlrev_b32_e32 v162, 16, v11
	v_and_b32_e32 v163, 0xffff0000, v11
	s_waitcnt vmcnt(32)
	v_lshlrev_b32_e32 v164, 16, v28
	v_and_b32_e32 v165, 0xffff0000, v28
	v_lshlrev_b32_e32 v166, 16, v29
	v_and_b32_e32 v167, 0xffff0000, v29
	v_lshlrev_b32_e32 v168, 16, v30
	v_and_b32_e32 v169, 0xffff0000, v30
	v_lshlrev_b32_e32 v170, 16, v31
	v_and_b32_e32 v171, 0xffff0000, v31
	v_lshlrev_b32_e32 v172, 16, v32
	v_and_b32_e32 v173, 0xffff0000, v32
	v_lshlrev_b32_e32 v174, 16, v33
	v_and_b32_e32 v175, 0xffff0000, v33
	v_lshlrev_b32_e32 v176, 16, v34
	v_and_b32_e32 v177, 0xffff0000, v34
	v_lshlrev_b32_e32 v178, 16, v35
	v_and_b32_e32 v179, 0xffff0000, v35
	v_pk_mul_f32 v[236:237], v[148:149], v[148:149]
	v_pk_fma_f32 v[236:237], v[150:151], v[150:151], v[236:237]
	v_pk_fma_f32 v[236:237], v[152:153], v[152:153], v[236:237]
	v_pk_fma_f32 v[236:237], v[154:155], v[154:155], v[236:237]
	v_pk_fma_f32 v[236:237], v[156:157], v[156:157], v[236:237]
	v_pk_fma_f32 v[236:237], v[158:159], v[158:159], v[236:237]
	v_pk_fma_f32 v[236:237], v[160:161], v[160:161], v[236:237]
	v_pk_fma_f32 v[236:237], v[162:163], v[162:163], v[236:237]
	v_pk_mul_f32 v[238:239], v[164:165], v[164:165]
	v_pk_fma_f32 v[238:239], v[166:167], v[166:167], v[238:239]
	v_pk_fma_f32 v[238:239], v[168:169], v[168:169], v[238:239]
	v_pk_fma_f32 v[238:239], v[170:171], v[170:171], v[238:239]
	v_pk_fma_f32 v[238:239], v[172:173], v[172:173], v[238:239]
	v_pk_fma_f32 v[238:239], v[174:175], v[174:175], v[238:239]
	v_pk_fma_f32 v[238:239], v[176:177], v[176:177], v[238:239]
	v_pk_fma_f32 v[238:239], v[178:179], v[178:179], v[238:239]
	v_add_f32_e32 v236, v236, v237
	v_add_f32_e32 v238, v238, v239
	s_nop 1
	v_add_f32_dpp v236, v236, v236 quad_perm:[1,0,3,2] row_mask:0xf bank_mask:0xf
	v_add_f32_dpp v238, v238, v238 quad_perm:[1,0,3,2] row_mask:0xf bank_mask:0xf
	s_nop 1
	v_add_f32_dpp v236, v236, v236 quad_perm:[2,3,0,1] row_mask:0xf bank_mask:0xf
	v_add_f32_dpp v238, v238, v238 quad_perm:[2,3,0,1] row_mask:0xf bank_mask:0xf
	s_nop 1
	v_add_f32_dpp v236, v236, v236 row_half_mirror row_mask:0xf bank_mask:0xf
	v_add_f32_dpp v238, v238, v238 row_half_mirror row_mask:0xf bank_mask:0xf
	s_nop 1
	v_add_f32_dpp v236, v236, v236 row_mirror row_mask:0xf bank_mask:0xf
	v_add_f32_dpp v238, v238, v238 row_mirror row_mask:0xf bank_mask:0xf
	s_nop 1
	v_add_f32_dpp v236, v236, v236 row_bcast:15 row_mask:0xa bank_mask:0xf
	v_add_f32_dpp v238, v238, v238 row_bcast:15 row_mask:0xa bank_mask:0xf
	s_nop 1
	v_add_f32_dpp v236, v236, v236 row_bcast:31 row_mask:0xc bank_mask:0xf
	v_add_f32_dpp v238, v238, v238 row_bcast:31 row_mask:0xc bank_mask:0xf
	s_nop 1
	v_readlane_b32 s2, v236, 63
	v_readlane_b32 s3, v238, 63
	s_nop 1
	v_mov_b32_e32 v240, s2
	v_mov_b32_e32 v242, s3
	v_fmamk_f32 v240, v240, 0x3a800000, v196
	v_fmamk_f32 v242, v242, 0x3a800000, v196
	v_rsq_f32_e32 v240, v240
	v_rsq_f32_e32 v242, v242
	s_nop 0
	v_pk_mul_f32 v[148:149], v[148:149], v[240:241] op_sel_hi:[1,0]
	v_pk_mul_f32 v[150:151], v[150:151], v[240:241] op_sel_hi:[1,0]
	v_pk_mul_f32 v[152:153], v[152:153], v[240:241] op_sel_hi:[1,0]
	v_pk_mul_f32 v[154:155], v[154:155], v[240:241] op_sel_hi:[1,0]
	v_pk_mul_f32 v[156:157], v[156:157], v[240:241] op_sel_hi:[1,0]
	v_pk_mul_f32 v[158:159], v[158:159], v[240:241] op_sel_hi:[1,0]
	v_pk_mul_f32 v[160:161], v[160:161], v[240:241] op_sel_hi:[1,0]
	v_pk_mul_f32 v[162:163], v[162:163], v[240:241] op_sel_hi:[1,0]
	v_pk_fma_f32 v[148:149], v[148:149], v[180:181], v[12:13]
	v_pk_fma_f32 v[150:151], v[150:151], v[182:183], v[14:15]
	v_pk_fma_f32 v[152:153], v[152:153], v[184:185], v[16:17]
	v_pk_fma_f32 v[154:155], v[154:155], v[186:187], v[18:19]
	v_pk_fma_f32 v[156:157], v[156:157], v[188:189], v[20:21]
	v_pk_fma_f32 v[158:159], v[158:159], v[190:191], v[22:23]
	v_pk_fma_f32 v[160:161], v[160:161], v[192:193], v[24:25]
	v_pk_fma_f32 v[162:163], v[162:163], v[194:195], v[26:27]
	v_pk_mul_f32 v[164:165], v[164:165], v[242:243] op_sel_hi:[1,0]
	v_pk_mul_f32 v[166:167], v[166:167], v[242:243] op_sel_hi:[1,0]
	v_pk_mul_f32 v[168:169], v[168:169], v[242:243] op_sel_hi:[1,0]
	v_pk_mul_f32 v[170:171], v[170:171], v[242:243] op_sel_hi:[1,0]
	v_pk_mul_f32 v[172:173], v[172:173], v[242:243] op_sel_hi:[1,0]
	v_pk_mul_f32 v[174:175], v[174:175], v[242:243] op_sel_hi:[1,0]
	v_pk_mul_f32 v[176:177], v[176:177], v[242:243] op_sel_hi:[1,0]
	v_pk_mul_f32 v[178:179], v[178:179], v[242:243] op_sel_hi:[1,0]
	v_pk_fma_f32 v[164:165], v[164:165], v[180:181], v[36:37]
	v_pk_fma_f32 v[166:167], v[166:167], v[182:183], v[38:39]
	v_pk_fma_f32 v[168:169], v[168:169], v[184:185], v[40:41]
	v_pk_fma_f32 v[170:171], v[170:171], v[186:187], v[42:43]
	v_pk_fma_f32 v[172:173], v[172:173], v[188:189], v[44:45]
	v_pk_fma_f32 v[174:175], v[174:175], v[190:191], v[46:47]
	v_pk_fma_f32 v[176:177], v[176:177], v[192:193], v[48:49]
	v_pk_fma_f32 v[178:179], v[178:179], v[194:195], v[50:51]
	v_pk_mul_f32 v[236:237], v[148:149], v[148:149]
	v_pk_fma_f32 v[236:237], v[150:151], v[150:151], v[236:237]
	v_pk_fma_f32 v[236:237], v[152:153], v[152:153], v[236:237]
	v_pk_fma_f32 v[236:237], v[154:155], v[154:155], v[236:237]
	v_pk_fma_f32 v[236:237], v[156:157], v[156:157], v[236:237]
	v_pk_fma_f32 v[236:237], v[158:159], v[158:159], v[236:237]
	v_pk_fma_f32 v[236:237], v[160:161], v[160:161], v[236:237]
	v_pk_fma_f32 v[236:237], v[162:163], v[162:163], v[236:237]
	v_pk_mul_f32 v[238:239], v[164:165], v[164:165]
	v_pk_fma_f32 v[238:239], v[166:167], v[166:167], v[238:239]
	v_pk_fma_f32 v[238:239], v[168:169], v[168:169], v[238:239]
	v_pk_fma_f32 v[238:239], v[170:171], v[170:171], v[238:239]
	v_pk_fma_f32 v[238:239], v[172:173], v[172:173], v[238:239]
	v_pk_fma_f32 v[238:239], v[174:175], v[174:175], v[238:239]
	v_pk_fma_f32 v[238:239], v[176:177], v[176:177], v[238:239]
	v_pk_fma_f32 v[238:239], v[178:179], v[178:179], v[238:239]
	v_add_f32_e32 v236, v236, v237
	v_add_f32_e32 v238, v238, v239
	s_nop 1
	v_add_f32_dpp v236, v236, v236 quad_perm:[1,0,3,2] row_mask:0xf bank_mask:0xf
	v_add_f32_dpp v238, v238, v238 quad_perm:[1,0,3,2] row_mask:0xf bank_mask:0xf
	s_nop 1
	v_add_f32_dpp v236, v236, v236 quad_perm:[2,3,0,1] row_mask:0xf bank_mask:0xf
	v_add_f32_dpp v238, v238, v238 quad_perm:[2,3,0,1] row_mask:0xf bank_mask:0xf
	s_nop 1
	v_add_f32_dpp v236, v236, v236 row_half_mirror row_mask:0xf bank_mask:0xf
	v_add_f32_dpp v238, v238, v238 row_half_mirror row_mask:0xf bank_mask:0xf
	s_nop 1
	v_add_f32_dpp v236, v236, v236 row_mirror row_mask:0xf bank_mask:0xf
	v_add_f32_dpp v238, v238, v238 row_mirror row_mask:0xf bank_mask:0xf
	s_nop 1
	v_add_f32_dpp v236, v236, v236 row_bcast:15 row_mask:0xa bank_mask:0xf
	v_add_f32_dpp v238, v238, v238 row_bcast:15 row_mask:0xa bank_mask:0xf
	s_nop 1
	v_add_f32_dpp v236, v236, v236 row_bcast:31 row_mask:0xc bank_mask:0xf
	v_add_f32_dpp v238, v238, v238 row_bcast:31 row_mask:0xc bank_mask:0xf
	s_nop 1
	v_readlane_b32 s2, v236, 63
	v_readlane_b32 s3, v238, 63
	s_nop 1
	v_mov_b32_e32 v240, s2
	v_mov_b32_e32 v242, s3
	v_fmamk_f32 v240, v240, 0x3a800000, v196
	v_fmamk_f32 v242, v242, 0x3a800000, v196
	v_rsq_f32_e32 v240, v240
	v_rsq_f32_e32 v242, v242
	s_nop 0
	v_pk_mul_f32 v[148:149], v[148:149], v[240:241] op_sel_hi:[1,0]
	v_pk_mul_f32 v[150:151], v[150:151], v[240:241] op_sel_hi:[1,0]
	v_pk_mul_f32 v[152:153], v[152:153], v[240:241] op_sel_hi:[1,0]
	v_pk_mul_f32 v[154:155], v[154:155], v[240:241] op_sel_hi:[1,0]
	v_pk_mul_f32 v[156:157], v[156:157], v[240:241] op_sel_hi:[1,0]
	v_pk_mul_f32 v[158:159], v[158:159], v[240:241] op_sel_hi:[1,0]
	v_pk_mul_f32 v[160:161], v[160:161], v[240:241] op_sel_hi:[1,0]
	v_pk_mul_f32 v[162:163], v[162:163], v[240:241] op_sel_hi:[1,0]
	v_pk_mul_f32 v[148:149], v[148:149], v[202:203]
	v_pk_mul_f32 v[150:151], v[150:151], v[204:205]
	v_pk_mul_f32 v[152:153], v[152:153], v[206:207]
	v_pk_mul_f32 v[154:155], v[154:155], v[208:209]
	v_pk_mul_f32 v[156:157], v[156:157], v[210:211]
	v_pk_mul_f32 v[158:159], v[158:159], v[212:213]
	v_pk_mul_f32 v[160:161], v[160:161], v[214:215]
	v_pk_mul_f32 v[162:163], v[162:163], v[216:217]
	v_cvt_pk_bf16_f32 v148, v148, v149
	v_cvt_pk_bf16_f32 v149, v150, v151
	v_cvt_pk_bf16_f32 v150, v152, v153
	v_cvt_pk_bf16_f32 v151, v154, v155
	v_cvt_pk_bf16_f32 v152, v156, v157
	v_cvt_pk_bf16_f32 v153, v158, v159
	v_cvt_pk_bf16_f32 v154, v160, v161
	v_cvt_pk_bf16_f32 v155, v162, v163
	s_add_u32 s26, s14, 0x3000000
	s_addc_u32 s27, s15, 0
	global_store_dwordx2 v245, v[148:149], s[26:27] offset:0
	global_store_dwordx2 v245, v[150:151], s[26:27] offset:512
	global_store_dwordx2 v245, v[152:153], s[26:27] offset:1024
	global_store_dwordx2 v245, v[154:155], s[26:27] offset:1536
	v_pk_mul_f32 v[164:165], v[164:165], v[242:243] op_sel_hi:[1,0]
	v_pk_mul_f32 v[166:167], v[166:167], v[242:243] op_sel_hi:[1,0]
	v_pk_mul_f32 v[168:169], v[168:169], v[242:243] op_sel_hi:[1,0]
	v_pk_mul_f32 v[170:171], v[170:171], v[242:243] op_sel_hi:[1,0]
	v_pk_mul_f32 v[172:173], v[172:173], v[242:243] op_sel_hi:[1,0]
	v_pk_mul_f32 v[174:175], v[174:175], v[242:243] op_sel_hi:[1,0]
	v_pk_mul_f32 v[176:177], v[176:177], v[242:243] op_sel_hi:[1,0]
	v_pk_mul_f32 v[178:179], v[178:179], v[242:243] op_sel_hi:[1,0]
	v_pk_mul_f32 v[164:165], v[164:165], v[202:203]
	v_pk_mul_f32 v[166:167], v[166:167], v[204:205]
	v_pk_mul_f32 v[168:169], v[168:169], v[206:207]
	v_pk_mul_f32 v[170:171], v[170:171], v[208:209]
	v_pk_mul_f32 v[172:173], v[172:173], v[210:211]
	v_pk_mul_f32 v[174:175], v[174:175], v[212:213]
	v_pk_mul_f32 v[176:177], v[176:177], v[214:215]
	v_pk_mul_f32 v[178:179], v[178:179], v[216:217]
	v_cvt_pk_bf16_f32 v164, v164, v165
	v_cvt_pk_bf16_f32 v165, v166, v167
	v_cvt_pk_bf16_f32 v166, v168, v169
	v_cvt_pk_bf16_f32 v167, v170, v171
	v_cvt_pk_bf16_f32 v168, v172, v173
	v_cvt_pk_bf16_f32 v169, v174, v175
	v_cvt_pk_bf16_f32 v170, v176, v177
	v_cvt_pk_bf16_f32 v171, v178, v179
	s_add_u32 s26, s14, 0x3400000
	s_addc_u32 s27, s15, 0
	global_store_dwordx2 v245, v[164:165], s[26:27] offset:0
	global_store_dwordx2 v245, v[166:167], s[26:27] offset:512
	global_store_dwordx2 v245, v[168:169], s[26:27] offset:1024
	global_store_dwordx2 v245, v[170:171], s[26:27] offset:1536
	s_waitcnt vmcnt(24)
	v_lshlrev_b32_e32 v148, 16, v52
	v_and_b32_e32 v149, 0xffff0000, v52
	v_lshlrev_b32_e32 v150, 16, v53
	v_and_b32_e32 v151, 0xffff0000, v53
	v_lshlrev_b32_e32 v152, 16, v54
	v_and_b32_e32 v153, 0xffff0000, v54
	v_lshlrev_b32_e32 v154, 16, v55
	v_and_b32_e32 v155, 0xffff0000, v55
	v_lshlrev_b32_e32 v156, 16, v56
	v_and_b32_e32 v157, 0xffff0000, v56
	v_lshlrev_b32_e32 v158, 16, v57
	v_and_b32_e32 v159, 0xffff0000, v57
	v_lshlrev_b32_e32 v160, 16, v58
	v_and_b32_e32 v161, 0xffff0000, v58
	v_lshlrev_b32_e32 v162, 16, v59
	v_and_b32_e32 v163, 0xffff0000, v59
	s_waitcnt vmcnt(16)
	v_lshlrev_b32_e32 v164, 16, v76
	v_and_b32_e32 v165, 0xffff0000, v76
	v_lshlrev_b32_e32 v166, 16, v77
	v_and_b32_e32 v167, 0xffff0000, v77
	v_lshlrev_b32_e32 v168, 16, v78
	v_and_b32_e32 v169, 0xffff0000, v78
	v_lshlrev_b32_e32 v170, 16, v79
	v_and_b32_e32 v171, 0xffff0000, v79
	v_lshlrev_b32_e32 v172, 16, v80
	v_and_b32_e32 v173, 0xffff0000, v80
	v_lshlrev_b32_e32 v174, 16, v81
	v_and_b32_e32 v175, 0xffff0000, v81
	v_lshlrev_b32_e32 v176, 16, v82
	v_and_b32_e32 v177, 0xffff0000, v82
	v_lshlrev_b32_e32 v178, 16, v83
	v_and_b32_e32 v179, 0xffff0000, v83
	v_pk_mul_f32 v[236:237], v[148:149], v[148:149]
	v_pk_fma_f32 v[236:237], v[150:151], v[150:151], v[236:237]
	v_pk_fma_f32 v[236:237], v[152:153], v[152:153], v[236:237]
	v_pk_fma_f32 v[236:237], v[154:155], v[154:155], v[236:237]
	v_pk_fma_f32 v[236:237], v[156:157], v[156:157], v[236:237]
	v_pk_fma_f32 v[236:237], v[158:159], v[158:159], v[236:237]
	v_pk_fma_f32 v[236:237], v[160:161], v[160:161], v[236:237]
	v_pk_fma_f32 v[236:237], v[162:163], v[162:163], v[236:237]
	v_pk_mul_f32 v[238:239], v[164:165], v[164:165]
	v_pk_fma_f32 v[238:239], v[166:167], v[166:167], v[238:239]
	v_pk_fma_f32 v[238:239], v[168:169], v[168:169], v[238:239]
	v_pk_fma_f32 v[238:239], v[170:171], v[170:171], v[238:239]
	v_pk_fma_f32 v[238:239], v[172:173], v[172:173], v[238:239]
	v_pk_fma_f32 v[238:239], v[174:175], v[174:175], v[238:239]
	v_pk_fma_f32 v[238:239], v[176:177], v[176:177], v[238:239]
	v_pk_fma_f32 v[238:239], v[178:179], v[178:179], v[238:239]
	v_add_f32_e32 v236, v236, v237
	v_add_f32_e32 v238, v238, v239
	s_nop 1
	v_add_f32_dpp v236, v236, v236 quad_perm:[1,0,3,2] row_mask:0xf bank_mask:0xf
	v_add_f32_dpp v238, v238, v238 quad_perm:[1,0,3,2] row_mask:0xf bank_mask:0xf
	s_nop 1
	v_add_f32_dpp v236, v236, v236 quad_perm:[2,3,0,1] row_mask:0xf bank_mask:0xf
	v_add_f32_dpp v238, v238, v238 quad_perm:[2,3,0,1] row_mask:0xf bank_mask:0xf
	s_nop 1
	v_add_f32_dpp v236, v236, v236 row_half_mirror row_mask:0xf bank_mask:0xf
	v_add_f32_dpp v238, v238, v238 row_half_mirror row_mask:0xf bank_mask:0xf
	s_nop 1
	v_add_f32_dpp v236, v236, v236 row_mirror row_mask:0xf bank_mask:0xf
	v_add_f32_dpp v238, v238, v238 row_mirror row_mask:0xf bank_mask:0xf
	s_nop 1
	v_add_f32_dpp v236, v236, v236 row_bcast:15 row_mask:0xa bank_mask:0xf
	v_add_f32_dpp v238, v238, v238 row_bcast:15 row_mask:0xa bank_mask:0xf
	s_nop 1
	v_add_f32_dpp v236, v236, v236 row_bcast:31 row_mask:0xc bank_mask:0xf
	v_add_f32_dpp v238, v238, v238 row_bcast:31 row_mask:0xc bank_mask:0xf
	s_nop 1
	v_readlane_b32 s2, v236, 63
	v_readlane_b32 s3, v238, 63
	s_nop 1
	v_mov_b32_e32 v240, s2
	v_mov_b32_e32 v242, s3
	v_fmamk_f32 v240, v240, 0x3a800000, v196
	v_fmamk_f32 v242, v242, 0x3a800000, v196
	v_rsq_f32_e32 v240, v240
	v_rsq_f32_e32 v242, v242
	s_nop 0
	v_pk_mul_f32 v[148:149], v[148:149], v[240:241] op_sel_hi:[1,0]
	v_pk_mul_f32 v[150:151], v[150:151], v[240:241] op_sel_hi:[1,0]
	v_pk_mul_f32 v[152:153], v[152:153], v[240:241] op_sel_hi:[1,0]
	v_pk_mul_f32 v[154:155], v[154:155], v[240:241] op_sel_hi:[1,0]
	v_pk_mul_f32 v[156:157], v[156:157], v[240:241] op_sel_hi:[1,0]
	v_pk_mul_f32 v[158:159], v[158:159], v[240:241] op_sel_hi:[1,0]
	v_pk_mul_f32 v[160:161], v[160:161], v[240:241] op_sel_hi:[1,0]
	v_pk_mul_f32 v[162:163], v[162:163], v[240:241] op_sel_hi:[1,0]
	v_pk_fma_f32 v[148:149], v[148:149], v[180:181], v[60:61]
	v_pk_fma_f32 v[150:151], v[150:151], v[182:183], v[62:63]
	v_pk_fma_f32 v[152:153], v[152:153], v[184:185], v[64:65]
	v_pk_fma_f32 v[154:155], v[154:155], v[186:187], v[66:67]
	v_pk_fma_f32 v[156:157], v[156:157], v[188:189], v[68:69]
	v_pk_fma_f32 v[158:159], v[158:159], v[190:191], v[70:71]
	v_pk_fma_f32 v[160:161], v[160:161], v[192:193], v[72:73]
	v_pk_fma_f32 v[162:163], v[162:163], v[194:195], v[74:75]
	v_pk_mul_f32 v[164:165], v[164:165], v[242:243] op_sel_hi:[1,0]
	v_pk_mul_f32 v[166:167], v[166:167], v[242:243] op_sel_hi:[1,0]
	v_pk_mul_f32 v[168:169], v[168:169], v[242:243] op_sel_hi:[1,0]
	v_pk_mul_f32 v[170:171], v[170:171], v[242:243] op_sel_hi:[1,0]
	v_pk_mul_f32 v[172:173], v[172:173], v[242:243] op_sel_hi:[1,0]
	v_pk_mul_f32 v[174:175], v[174:175], v[242:243] op_sel_hi:[1,0]
	v_pk_mul_f32 v[176:177], v[176:177], v[242:243] op_sel_hi:[1,0]
	v_pk_mul_f32 v[178:179], v[178:179], v[242:243] op_sel_hi:[1,0]
	v_pk_fma_f32 v[164:165], v[164:165], v[180:181], v[84:85]
	v_pk_fma_f32 v[166:167], v[166:167], v[182:183], v[86:87]
	v_pk_fma_f32 v[168:169], v[168:169], v[184:185], v[88:89]
	v_pk_fma_f32 v[170:171], v[170:171], v[186:187], v[90:91]
	v_pk_fma_f32 v[172:173], v[172:173], v[188:189], v[92:93]
	v_pk_fma_f32 v[174:175], v[174:175], v[190:191], v[94:95]
	v_pk_fma_f32 v[176:177], v[176:177], v[192:193], v[96:97]
	v_pk_fma_f32 v[178:179], v[178:179], v[194:195], v[98:99]
	v_pk_mul_f32 v[236:237], v[148:149], v[148:149]
	v_pk_fma_f32 v[236:237], v[150:151], v[150:151], v[236:237]
	v_pk_fma_f32 v[236:237], v[152:153], v[152:153], v[236:237]
	v_pk_fma_f32 v[236:237], v[154:155], v[154:155], v[236:237]
	v_pk_fma_f32 v[236:237], v[156:157], v[156:157], v[236:237]
	v_pk_fma_f32 v[236:237], v[158:159], v[158:159], v[236:237]
	v_pk_fma_f32 v[236:237], v[160:161], v[160:161], v[236:237]
	v_pk_fma_f32 v[236:237], v[162:163], v[162:163], v[236:237]
	v_pk_mul_f32 v[238:239], v[164:165], v[164:165]
	v_pk_fma_f32 v[238:239], v[166:167], v[166:167], v[238:239]
	v_pk_fma_f32 v[238:239], v[168:169], v[168:169], v[238:239]
	v_pk_fma_f32 v[238:239], v[170:171], v[170:171], v[238:239]
	v_pk_fma_f32 v[238:239], v[172:173], v[172:173], v[238:239]
	v_pk_fma_f32 v[238:239], v[174:175], v[174:175], v[238:239]
	v_pk_fma_f32 v[238:239], v[176:177], v[176:177], v[238:239]
	v_pk_fma_f32 v[238:239], v[178:179], v[178:179], v[238:239]
	v_add_f32_e32 v236, v236, v237
	v_add_f32_e32 v238, v238, v239
	s_nop 1
	v_add_f32_dpp v236, v236, v236 quad_perm:[1,0,3,2] row_mask:0xf bank_mask:0xf
	v_add_f32_dpp v238, v238, v238 quad_perm:[1,0,3,2] row_mask:0xf bank_mask:0xf
	s_nop 1
	v_add_f32_dpp v236, v236, v236 quad_perm:[2,3,0,1] row_mask:0xf bank_mask:0xf
	v_add_f32_dpp v238, v238, v238 quad_perm:[2,3,0,1] row_mask:0xf bank_mask:0xf
	s_nop 1
	v_add_f32_dpp v236, v236, v236 row_half_mirror row_mask:0xf bank_mask:0xf
	v_add_f32_dpp v238, v238, v238 row_half_mirror row_mask:0xf bank_mask:0xf
	s_nop 1
	v_add_f32_dpp v236, v236, v236 row_mirror row_mask:0xf bank_mask:0xf
	v_add_f32_dpp v238, v238, v238 row_mirror row_mask:0xf bank_mask:0xf
	s_nop 1
	v_add_f32_dpp v236, v236, v236 row_bcast:15 row_mask:0xa bank_mask:0xf
	v_add_f32_dpp v238, v238, v238 row_bcast:15 row_mask:0xa bank_mask:0xf
	s_nop 1
	v_add_f32_dpp v236, v236, v236 row_bcast:31 row_mask:0xc bank_mask:0xf
	v_add_f32_dpp v238, v238, v238 row_bcast:31 row_mask:0xc bank_mask:0xf
	s_nop 1
	v_readlane_b32 s2, v236, 63
	v_readlane_b32 s3, v238, 63
	s_nop 1
	v_mov_b32_e32 v240, s2
	v_mov_b32_e32 v242, s3
	v_fmamk_f32 v240, v240, 0x3a800000, v196
	v_fmamk_f32 v242, v242, 0x3a800000, v196
	v_rsq_f32_e32 v240, v240
	v_rsq_f32_e32 v242, v242
	s_nop 0
	v_pk_mul_f32 v[148:149], v[148:149], v[240:241] op_sel_hi:[1,0]
	v_pk_mul_f32 v[150:151], v[150:151], v[240:241] op_sel_hi:[1,0]
	v_pk_mul_f32 v[152:153], v[152:153], v[240:241] op_sel_hi:[1,0]
	v_pk_mul_f32 v[154:155], v[154:155], v[240:241] op_sel_hi:[1,0]
	v_pk_mul_f32 v[156:157], v[156:157], v[240:241] op_sel_hi:[1,0]
	v_pk_mul_f32 v[158:159], v[158:159], v[240:241] op_sel_hi:[1,0]
	v_pk_mul_f32 v[160:161], v[160:161], v[240:241] op_sel_hi:[1,0]
	v_pk_mul_f32 v[162:163], v[162:163], v[240:241] op_sel_hi:[1,0]
	v_pk_mul_f32 v[148:149], v[148:149], v[202:203]
	v_pk_mul_f32 v[150:151], v[150:151], v[204:205]
	v_pk_mul_f32 v[152:153], v[152:153], v[206:207]
	v_pk_mul_f32 v[154:155], v[154:155], v[208:209]
	v_pk_mul_f32 v[156:157], v[156:157], v[210:211]
	v_pk_mul_f32 v[158:159], v[158:159], v[212:213]
	v_pk_mul_f32 v[160:161], v[160:161], v[214:215]
	v_pk_mul_f32 v[162:163], v[162:163], v[216:217]
	v_cvt_pk_bf16_f32 v148, v148, v149
	v_cvt_pk_bf16_f32 v149, v150, v151
	v_cvt_pk_bf16_f32 v150, v152, v153
	v_cvt_pk_bf16_f32 v151, v154, v155
	v_cvt_pk_bf16_f32 v152, v156, v157
	v_cvt_pk_bf16_f32 v153, v158, v159
	v_cvt_pk_bf16_f32 v154, v160, v161
	v_cvt_pk_bf16_f32 v155, v162, v163
	s_add_u32 s26, s14, 0x3800000
	s_addc_u32 s27, s15, 0
	global_store_dwordx2 v245, v[148:149], s[26:27] offset:0
	global_store_dwordx2 v245, v[150:151], s[26:27] offset:512
	global_store_dwordx2 v245, v[152:153], s[26:27] offset:1024
	global_store_dwordx2 v245, v[154:155], s[26:27] offset:1536
	v_pk_mul_f32 v[164:165], v[164:165], v[242:243] op_sel_hi:[1,0]
	v_pk_mul_f32 v[166:167], v[166:167], v[242:243] op_sel_hi:[1,0]
	v_pk_mul_f32 v[168:169], v[168:169], v[242:243] op_sel_hi:[1,0]
	v_pk_mul_f32 v[170:171], v[170:171], v[242:243] op_sel_hi:[1,0]
	v_pk_mul_f32 v[172:173], v[172:173], v[242:243] op_sel_hi:[1,0]
	v_pk_mul_f32 v[174:175], v[174:175], v[242:243] op_sel_hi:[1,0]
	v_pk_mul_f32 v[176:177], v[176:177], v[242:243] op_sel_hi:[1,0]
	v_pk_mul_f32 v[178:179], v[178:179], v[242:243] op_sel_hi:[1,0]
	v_pk_mul_f32 v[164:165], v[164:165], v[202:203]
	v_pk_mul_f32 v[166:167], v[166:167], v[204:205]
	v_pk_mul_f32 v[168:169], v[168:169], v[206:207]
	v_pk_mul_f32 v[170:171], v[170:171], v[208:209]
	v_pk_mul_f32 v[172:173], v[172:173], v[210:211]
	v_pk_mul_f32 v[174:175], v[174:175], v[212:213]
	v_pk_mul_f32 v[176:177], v[176:177], v[214:215]
	v_pk_mul_f32 v[178:179], v[178:179], v[216:217]
	v_cvt_pk_bf16_f32 v164, v164, v165
	v_cvt_pk_bf16_f32 v165, v166, v167
	v_cvt_pk_bf16_f32 v166, v168, v169
	v_cvt_pk_bf16_f32 v167, v170, v171
	v_cvt_pk_bf16_f32 v168, v172, v173
	v_cvt_pk_bf16_f32 v169, v174, v175
	v_cvt_pk_bf16_f32 v170, v176, v177
	v_cvt_pk_bf16_f32 v171, v178, v179
	s_add_u32 s26, s14, 0x3c00000
	s_addc_u32 s27, s15, 0
	global_store_dwordx2 v245, v[164:165], s[26:27] offset:0
	global_store_dwordx2 v245, v[166:167], s[26:27] offset:512
	global_store_dwordx2 v245, v[168:169], s[26:27] offset:1024
	global_store_dwordx2 v245, v[170:171], s[26:27] offset:1536
	s_cmpk_ge_u32 s1, 0x100
	s_cbranch_scc1 .Lrow6_done
	s_cmpk_ge_u32 s1, 16
	s_cbranch_scc1 .Lrow6_zero
	s_mov_b64 s[22:23], s[16:17]
	s_mov_b64 s[24:25], s[18:19]
	global_load_dwordx2 v[4:5], v245, s[22:23] offset:0
	global_load_dwordx2 v[6:7], v245, s[22:23] offset:512
	global_load_dwordx2 v[8:9], v245, s[22:23] offset:1024
	global_load_dwordx2 v[10:11], v245, s[22:23] offset:1536
	global_load_dwordx4 v[12:15], v244, s[24:25] offset:0
	global_load_dwordx4 v[16:19], v244, s[24:25] offset:1024
	global_load_dwordx4 v[20:23], v244, s[24:25] offset:2048
	global_load_dwordx4 v[24:27], v244, s[24:25] offset:3072
	s_waitcnt vmcnt(0)
	v_lshlrev_b32_e32 v148, 16, v4
	v_and_b32_e32 v149, 0xffff0000, v4
	v_lshlrev_b32_e32 v150, 16, v5
	v_and_b32_e32 v151, 0xffff0000, v5
	v_lshlrev_b32_e32 v152, 16, v6
	v_and_b32_e32 v153, 0xffff0000, v6
	v_lshlrev_b32_e32 v154, 16, v7
	v_and_b32_e32 v155, 0xffff0000, v7
	v_lshlrev_b32_e32 v156, 16, v8
	v_and_b32_e32 v157, 0xffff0000, v8
	v_lshlrev_b32_e32 v158, 16, v9
	v_and_b32_e32 v159, 0xffff0000, v9
	v_lshlrev_b32_e32 v160, 16, v10
	v_and_b32_e32 v161, 0xffff0000, v10
	v_lshlrev_b32_e32 v162, 16, v11
	v_and_b32_e32 v163, 0xffff0000, v11
	v_pk_mul_f32 v[236:237], v[148:149], v[148:149]
	v_pk_fma_f32 v[236:237], v[150:151], v[150:151], v[236:237]
	v_pk_fma_f32 v[236:237], v[152:153], v[152:153], v[236:237]
	v_pk_fma_f32 v[236:237], v[154:155], v[154:155], v[236:237]
	v_pk_fma_f32 v[236:237], v[156:157], v[156:157], v[236:237]
	v_pk_fma_f32 v[236:237], v[158:159], v[158:159], v[236:237]
	v_pk_fma_f32 v[236:237], v[160:161], v[160:161], v[236:237]
	v_pk_fma_f32 v[236:237], v[162:163], v[162:163], v[236:237]
	v_add_f32_e32 v236, v236, v237
	s_nop 1
	v_add_f32_dpp v236, v236, v236 quad_perm:[1,0,3,2] row_mask:0xf bank_mask:0xf
	s_nop 1
	v_add_f32_dpp v236, v236, v236 quad_perm:[2,3,0,1] row_mask:0xf bank_mask:0xf
	s_nop 1
	v_add_f32_dpp v236, v236, v236 row_half_mirror row_mask:0xf bank_mask:0xf
	s_nop 1
	v_add_f32_dpp v236, v236, v236 row_mirror row_mask:0xf bank_mask:0xf
	s_nop 1
	v_add_f32_dpp v236, v236, v236 row_bcast:15 row_mask:0xa bank_mask:0xf
	s_nop 1
	v_add_f32_dpp v236, v236, v236 row_bcast:31 row_mask:0xc bank_mask:0xf
	s_nop 1
	v_readlane_b32 s2, v236, 63
	s_nop 1
	v_mov_b32_e32 v240, s2
	v_fmamk_f32 v240, v240, 0x3a800000, v196
	v_rsq_f32_e32 v240, v240
	s_nop 0
	v_pk_mul_f32 v[148:149], v[148:149], v[240:241] op_sel_hi:[1,0]
	v_pk_mul_f32 v[150:151], v[150:151], v[240:241] op_sel_hi:[1,0]
	v_pk_mul_f32 v[152:153], v[152:153], v[240:241] op_sel_hi:[1,0]
	v_pk_mul_f32 v[154:155], v[154:155], v[240:241] op_sel_hi:[1,0]
	v_pk_mul_f32 v[156:157], v[156:157], v[240:241] op_sel_hi:[1,0]
	v_pk_mul_f32 v[158:159], v[158:159], v[240:241] op_sel_hi:[1,0]
	v_pk_mul_f32 v[160:161], v[160:161], v[240:241] op_sel_hi:[1,0]
	v_pk_mul_f32 v[162:163], v[162:163], v[240:241] op_sel_hi:[1,0]
	v_pk_fma_f32 v[148:149], v[148:149], v[180:181], v[12:13]
	v_pk_fma_f32 v[150:151], v[150:151], v[182:183], v[14:15]
	v_pk_fma_f32 v[152:153], v[152:153], v[184:185], v[16:17]
	v_pk_fma_f32 v[154:155], v[154:155], v[186:187], v[18:19]
	v_pk_fma_f32 v[156:157], v[156:157], v[188:189], v[20:21]
	v_pk_fma_f32 v[158:159], v[158:159], v[190:191], v[22:23]
	v_pk_fma_f32 v[160:161], v[160:161], v[192:193], v[24:25]
	v_pk_fma_f32 v[162:163], v[162:163], v[194:195], v[26:27]
	v_pk_mul_f32 v[236:237], v[148:149], v[148:149]
	v_pk_fma_f32 v[236:237], v[150:151], v[150:151], v[236:237]
	v_pk_fma_f32 v[236:237], v[152:153], v[152:153], v[236:237]
	v_pk_fma_f32 v[236:237], v[154:155], v[154:155], v[236:237]
	v_pk_fma_f32 v[236:237], v[156:157], v[156:157], v[236:237]
	v_pk_fma_f32 v[236:237], v[158:159], v[158:159], v[236:237]
	v_pk_fma_f32 v[236:237], v[160:161], v[160:161], v[236:237]
	v_pk_fma_f32 v[236:237], v[162:163], v[162:163], v[236:237]
	v_add_f32_e32 v236, v236, v237
	s_nop 1
	v_add_f32_dpp v236, v236, v236 quad_perm:[1,0,3,2] row_mask:0xf bank_mask:0xf
	s_nop 1
	v_add_f32_dpp v236, v236, v236 quad_perm:[2,3,0,1] row_mask:0xf bank_mask:0xf
	s_nop 1
	v_add_f32_dpp v236, v236, v236 row_half_mirror row_mask:0xf bank_mask:0xf
	s_nop 1
	v_add_f32_dpp v236, v236, v236 row_mirror row_mask:0xf bank_mask:0xf
	s_nop 1
	v_add_f32_dpp v236, v236, v236 row_bcast:15 row_mask:0xa bank_mask:0xf
	s_nop 1
	v_add_f32_dpp v236, v236, v236 row_bcast:31 row_mask:0xc bank_mask:0xf
	s_nop 1
	v_readlane_b32 s2, v236, 63
	s_nop 1
	v_mov_b32_e32 v240, s2
	v_fmamk_f32 v240, v240, 0x3a800000, v196
	v_rsq_f32_e32 v240, v240
	s_nop 0
	v_pk_mul_f32 v[148:149], v[148:149], v[240:241] op_sel_hi:[1,0]
	v_pk_mul_f32 v[150:151], v[150:151], v[240:241] op_sel_hi:[1,0]
	v_pk_mul_f32 v[152:153], v[152:153], v[240:241] op_sel_hi:[1,0]
	v_pk_mul_f32 v[154:155], v[154:155], v[240:241] op_sel_hi:[1,0]
	v_pk_mul_f32 v[156:157], v[156:157], v[240:241] op_sel_hi:[1,0]
	v_pk_mul_f32 v[158:159], v[158:159], v[240:241] op_sel_hi:[1,0]
	v_pk_mul_f32 v[160:161], v[160:161], v[240:241] op_sel_hi:[1,0]
	v_pk_mul_f32 v[162:163], v[162:163], v[240:241] op_sel_hi:[1,0]
	v_pk_mul_f32 v[148:149], v[148:149], v[202:203]
	v_pk_mul_f32 v[150:151], v[150:151], v[204:205]
	v_pk_mul_f32 v[152:153], v[152:153], v[206:207]
	v_pk_mul_f32 v[154:155], v[154:155], v[208:209]
	v_pk_mul_f32 v[156:157], v[156:157], v[210:211]
	v_pk_mul_f32 v[158:159], v[158:159], v[212:213]
	v_pk_mul_f32 v[160:161], v[160:161], v[214:215]
	v_pk_mul_f32 v[162:163], v[162:163], v[216:217]
	v_cvt_pk_bf16_f32 v148, v148, v149
	v_cvt_pk_bf16_f32 v149, v150, v151
	v_cvt_pk_bf16_f32 v150, v152, v153
	v_cvt_pk_bf16_f32 v151, v154, v155
	v_cvt_pk_bf16_f32 v152, v156, v157
	v_cvt_pk_bf16_f32 v153, v158, v159
	v_cvt_pk_bf16_f32 v154, v160, v161
	v_cvt_pk_bf16_f32 v155, v162, v163
	s_mov_b64 s[26:27], s[20:21]
	global_store_dwordx2 v245, v[148:149], s[26:27] offset:0
	global_store_dwordx2 v245, v[150:151], s[26:27] offset:512
	global_store_dwordx2 v245, v[152:153], s[26:27] offset:1024
	global_store_dwordx2 v245, v[154:155], s[26:27] offset:1536
	s_branch .Lrow6_done
